# v17: attention K and V tiles both staged HBM->LDS directly (no register staging, no ds_write)
# baseline (speedup 1.0000x reference)
; __device__ __forceinline__ unsigned cvtpk(float lo, float hi) { f32x2 v = {lo, hi}; bf16x2_t b = __builtin_convertvector(v, bf16x2_t); return *(unsigned*)&b; }
; __device__ __forceinline__ float lo16(unsigned w) { return __uint_as_float(w << 16); }
; __device__ void phase_attn(const Params& p, char* lds) {
;     ...
;   const int tid = threadIdx.x, wid = tid >> 6, lane = tid & 63, r32 = lane & 31, hi = lane >> 5;
;   char* V_lds = lds; char* K_lds = lds + AT_KOFF;
;   float* wsl = (float*)(lds + AT_WOFF) + wid * 64; float* li_l = wsl; float* al_l = wsl + 32;
;   const int skey = tid >> 3, sc8 = (tid & 7) * 8;
;   const int pkey = (tid & 255) >> 2, pc8 = (tid & 3) * 8;
;   const int vst = v_st(skey, sc8), kst = skey * AT_KROW + sc8 * 2, pst = pkey * AT_KROW + (64 + pc8) * 2;
;   const int vb0 = (int)(uintptr_t)V_lds + v_rd_base(lane);
;   const int nitems = NB * 16 * 32;
;   const int xcd = blockIdx.x & 7, slot = blockIdx.x >> 3, per = gridDim.x >> 3;
;   for (int it = slot; it < nitems / 8; it += per) {
;     const int pair = (it >> 5) * 8 + xcd, qblk = it & 31;
;     const int b = pair >> 4, h = pair & 15;
;     const size_t row0 = (size_t)b * TL;
;     const size_t qrow = row0 + qblk * 256 + wid * 32 + r32;
;     const bf16_t* Kh = KVg + row0 * 2048 + h * 128;
;     const bf16_t* Kp = KPg + row0 * 32;
;     float m_reg = 0.f, l_reg = 0.f;
;     f32x16 o[2];
; #pragma unroll
;     for (int dd = 0; dd < 2; ++dd)
; #pragma unroll
;       for (int r = 0; r < 16; ++r) o[dd][r] = 0.f;
;     bf16x8 qr[6];
;     {
;       const bf16_t* Qw = Qg + qrow * 1536 + h * 96 + hi * 8;
; #pragma unroll
;       for (int d0 = 0; d0 < 6; ++d0) qr[d0] = *(const bf16x8*)(Qw + d0 * 16);
;       const int t = qblk * 256 + wid * 32 + r32;
;       const f32x2* tb = rope + (hi ? (t & 63) : (t >> 6)) * 8;
;       const u32x4 x1 = *(const u32x4*)&qr[4], x2 = *(const u32x4*)&qr[5];
;       u32x4 n1, n2;
; #pragma unroll
;       for (int q = 0; q < 4; ++q) {
;         const f32x2 csA = tb[2 * q], csB = tb[2 * q + 1];
;         const float a0 = lo16(x1[q]), a1 = hi16(x1[q]), b0 = lo16(x2[q]), b1 = hi16(x2[q]);
;         n1[q] = cvtpk(a0 * csA[0] - b0 * csA[1], a1 * csB[0] - b1 * csB[1]);
;         n2[q] = cvtpk(a0 * csA[1] + b0 * csA[0], a1 * csB[1] + b1 * csB[0]);
;       }
;       qr[4] = *(bf16x8*)&n1; qr[5] = *(bf16x8*)&n2;
;     }
;     struct { bf16x8 vs, ks, ps; } sr_[2];
.LBB0_991:
	s_or_b64 exec, exec, s[4:5]
	s_cmpk_gt_u32 s3, 0xfff
	s_waitcnt vmcnt(7)
	v_and_b32_e32 v128, 56, v183
	v_lshlrev_b32_e32 v168, 11, v161
	s_barrier
	v_and_b32_e32 v175, 63, v178
	v_and_b32_e32 v183, 31, v178
	v_lshrrev_b32_e32 v228, 5, v175
	v_readfirstlane_b32 s14, v178
	v_lshrrev_b32_e32 v229, 3, v178
	v_and_b32_e32 v230, 7, v178
	s_lshr_b32 s14, s14, 6
	s_lshr_b32 s15, s14, 2
	s_and_b32 s43, s3, 7
	s_mov_b32 s23, 0x453a4f54
	v_lshlrev_b32_e32 v129, 4, v230
	v_lshl_or_b32 v129, v229, 12, v129
	v_mul_u32_u24_e32 v167, 0xd0, v229
	v_lshl_add_u32 v167, v230, 4, v167
	v_add_u32_e32 v167, 0x10000, v167
	v_bfe_u32 v131, v175, 2, 3
	v_lshl_add_u32 v131, s14, 3, v131
	v_lshlrev_b32_e32 v131, 12, v131
	v_lshlrev_b32_e32 v174, 2, v228
	v_and_or_b32 v174, v175, 3, v174
	v_lshl_add_u32 v131, v174, 4, v131
	v_add_u32_e32 v131, 0x80, v131
	s_lshl_b32 s40, s14, 11
	s_add_i32 s41, s14, 0
	s_lshl_b32 s16, s41, 6
	s_lshl_b32 s41, s41, 10
	v_add_u32_e32 v229, s16, v175
	v_mul_u32_u24_e32 v230, 0x13b2, v229
	v_lshrrev_b32_e32 v230, 16, v230
	v_mul_u32_u24_e32 v174, 13, v230
	v_sub_u32_e32 v229, v229, v174
	v_lshlrev_b32_e32 v249, 12, v230
	v_lshl_add_u32 v249, v229, 4, v249
	v_lshlrev_b32_e32 v174, 6, v230
	v_lshl_add_u32 v174, v229, 4, v174
	v_subrev_u32_e32 v174, 0x80, v174
	v_cmp_eq_u32_e32 vcc, 12, v229
	s_nop 1
	v_cndmask_b32_e64 v249, v249, 0, vcc
	v_cmp_lt_u32_e32 vcc, 7, v229
	s_mov_b64 s[44:45], vcc
	v_cmp_gt_u32_e32 vcc, 12, v229
	s_and_b64 s[44:45], s[44:45], vcc
	s_nop 1
	v_cndmask_b32_e64 v249, v249, v174, s[44:45]
	v_mov_b32_e32 v248, 0x40000
	v_mov_b32_e32 v174, 0x1000
	v_cndmask_b32_e64 v248, v248, v174, s[44:45]
	s_add_i32 s30, s14, 8
	s_lshl_b32 s16, s30, 6
	s_lshl_b32 s30, s30, 10
	v_add_u32_e32 v229, s16, v175
	v_mul_u32_u24_e32 v230, 0x13b2, v229
	v_lshrrev_b32_e32 v230, 16, v230
	v_mul_u32_u24_e32 v174, 13, v230
	v_sub_u32_e32 v229, v229, v174
	v_lshlrev_b32_e32 v253, 12, v230
	v_lshl_add_u32 v253, v229, 4, v253
	v_lshlrev_b32_e32 v174, 6, v230
	v_lshl_add_u32 v174, v229, 4, v174
	v_subrev_u32_e32 v174, 0x80, v174
	v_cmp_eq_u32_e32 vcc, 12, v229
	s_nop 1
	v_cndmask_b32_e64 v253, v253, 0, vcc
	v_cmp_lt_u32_e32 vcc, 7, v229
	s_mov_b64 s[46:47], vcc
	v_cmp_gt_u32_e32 vcc, 12, v229
	s_and_b64 s[46:47], s[46:47], vcc
	s_nop 1
	v_cndmask_b32_e64 v253, v253, v174, s[46:47]
	v_mov_b32_e32 v252, 0x40000
	v_mov_b32_e32 v174, 0x1000
	v_cndmask_b32_e64 v252, v252, v174, s[46:47]
	v_and_b32_e32 v174, 3, v178
	v_bfe_u32 v229, v178, 2, 6
	v_lshlrev_b32_e32 v130, 4, v174
	v_lshl_or_b32 v130, v229, 6, v130
	v_mul_u32_u24_e32 v169, 0xd0, v229
	v_lshl_add_u32 v169, v174, 4, v169
	v_add_u32_e32 v169, 0x10080, v169
	v_mul_u32_u24_e32 v170, 0xd0, v183
	v_lshl_add_u32 v170, v228, 4, v170
	v_add_u32_e32 v170, 0x10000, v170
	v_and_b32_e32 v174, 3, v175
	v_lshlrev_b32_e32 v174, 3, v174
	v_mov_b32_e32 v171, v174
	v_bfe_u32 v174, v175, 2, 2
	v_lshl_or_b32 v171, v174, 6, v171
	v_bfe_u32 v174, v175, 4, 1
	v_lshl_or_b32 v171, v174, 5, v171
	v_lshl_or_b32 v171, v228, 8, v171
	s_lshl_b32 s16, s14, 5
	v_add_u32_e32 v174, s16, v183
	v_mul_u32_u24_e32 v234, 0xc00, v174
	v_lshl_add_u32 v234, v228, 4, v234
	v_lshlrev_b32_e32 v235, 2, v228
	v_add_u32_e32 v235, s16, v235
	v_lshlrev_b32_e32 v235, 11, v235
	v_lshl_add_u32 v235, v183, 1, v235
	s_lshl_b32 s17, s14, 8
	s_add_i32 s17, s17, 0x1d000
	v_lshl_add_u32 v244, v183, 2, s17
	v_lshl_add_u32 v245, v228, 4, s17
	s_add_u32 s34, s86, 0x3d796000
	s_addc_u32 s35, s87, 0
	s_lshr_b32 s12, s3, 3
.Lat_item:
	s_lshr_b32 s16, s12, 5
	s_lshl_b32 s16, s16, 3
	s_add_i32 s16, s16, s43
	s_and_b32 s20, s12, 31
	s_lshr_b32 s22, s16, 4
	s_and_b32 s21, s16, 15
	s_mul_i32 s17, s22, 0x2100000
	s_lshl_b32 s18, s21, 8
	s_add_i32 s17, s17, s18
	s_add_u32 s17, s17, 0x29400000
	s_add_u32 s4, s86, s17
	s_addc_u32 s5, s87, 0
	s_mul_i32 s17, s22, 0x84000
	s_add_u32 s17, s17, 0x1de80000
	s_add_u32 s6, s86, s17
	s_addc_u32 s7, s87, 0
	s_mul_i32 s17, s22, 0x2100
	s_lshl_b32 s18, s20, 8
	s_add_i32 s17, s17, s18
	s_mul_i32 s18, s17, 0xc00
	s_mul_i32 s19, s21, 0xc0
	s_add_i32 s18, s18, s19
	s_add_u32 s18, s18, 0x8400000
	s_add_u32 s10, s86, s18
	s_addc_u32 s11, s87, 0
	s_lshl_b32 s18, s17, 11
	s_lshl_b32 s19, s21, 7
	s_add_i32 s18, s18, s19
	s_add_u32 s18, s18, 0x21000000
	s_add_u32 s28, s86, s18
	s_addc_u32 s29, s87, 0
	global_load_dwordx4 v[80:83], v234, s[10:11] offset:0
	global_load_dwordx4 v[84:87], v234, s[10:11] offset:32
	global_load_dwordx4 v[88:91], v234, s[10:11] offset:64
	global_load_dwordx4 v[92:95], v234, s[10:11] offset:96
	global_load_dwordx4 v[96:99], v234, s[10:11] offset:128
	global_load_dwordx4 v[100:103], v234, s[10:11] offset:160
	s_and_b32 s16, s14, 1
	s_lshl_b32 s16, s16, 5
	v_and_b32_e32 v183, 31, v178
	v_add_u32_e32 v183, s16, v183
	v_lshlrev_b32_e32 v183, 6, v183
	s_lshl_b32 s16, s20, 2
	s_lshr_b32 s17, s14, 1
	s_add_i32 s16, s16, s17
	s_lshl_b32 s16, s16, 6
	v_mov_b32_e32 v228, s16
	v_and_b32_e32 v229, 32, v178
	v_cmp_ne_u32_e32 vcc, 0, v229
	s_nop 1
	v_cndmask_b32_e32 v183, v228, v183, vcc
	global_load_dwordx4 v[32:35], v183, s[34:35] offset:0
	global_load_dwordx4 v[36:39], v183, s[34:35] offset:16
	global_load_dwordx4 v[40:43], v183, s[34:35] offset:32
	global_load_dwordx4 v[44:47], v183, s[34:35] offset:48
	s_barrier
	s_mov_b64 s[36:37], s[4:5]
	v_mov_b32_e32 v230, s6
	v_mov_b32_e32 v181, s7
	v_mov_b32_e32 v246, s4
	v_mov_b32_e32 v247, s5
	v_cndmask_b32_e64 v246, v246, v230, s[44:45]
	v_cndmask_b32_e64 v247, v247, v181, s[44:45]
	v_add_co_u32_e32 v246, vcc, v249, v246
	v_addc_co_u32_e32 v247, vcc, 0, v247, vcc
	v_mov_b32_e32 v250, s4
	v_mov_b32_e32 v251, s5
	v_cndmask_b32_e64 v250, v250, v230, s[46:47]
	v_cndmask_b32_e64 v251, v251, v181, s[46:47]
	v_add_co_u32_e32 v250, vcc, v253, v250
	v_addc_co_u32_e32 v251, vcc, 0, v251, vcc
	s_add_i32 m0, s41, 0x10000
	s_cmp_lt_u32 s14, 5
	global_load_lds_dwordx4 v[246:247], off
	v_add_co_u32_e32 v246, vcc, v248, v246
	v_addc_co_u32_e32 v247, vcc, 0, v247, vcc
	s_cbranch_scc0 .Lat_kd1
	s_add_i32 m0, s30, 0x10000
	s_nop 0
	global_load_lds_dwordx4 v[250:251], off
; __device__ __forceinline__ unsigned cvtpk(float lo, float hi) { f32x2 v = {lo, hi}; bf16x2_t b = __builtin_convertvector(v, bf16x2_t); return *(unsigned*)&b; }
; __device__ __forceinline__ float lo16(unsigned w) { return __uint_as_float(w << 16); }
; __device__ __forceinline__ float hi16(unsigned w) { return __uint_as_float(w & 0xffff0000u); }
; #define SLOAD(i, k0) do { sr_[i].vs = *(const bf16x8*)(Kh + (size_t)((k0) + skey) * 2048 + 64 + sc8); \
;     sr_[i].ks = *(const bf16x8*)(Kh + (size_t)((k0) + skey) * 2048 + sc8); \
;     sr_[i].ps = *(const bf16x8*)(Kp + (size_t)((k0) + pkey) * 32 + pc8); } while (0)
; #define SWRITE(bb, i) do { *(bf16x8*)(V_lds + (bb) * AT_SHMV + vst) = sr_[i].vs; \
;     *(bf16x8*)(K_lds + (bb) * AT_SHMK + kst) = sr_[i].ks; \
;     *(bf16x8*)(K_lds + (bb) * AT_SHMK + pst) = sr_[i].ps; } while (0)
; #define SWAIT() asm volatile("s_waitcnt vmcnt(3)" ::: "memory")
; __device__ void phase_attn(const Params& p, char* lds) {
;     ...
;     f32x16 o[2];
; #pragma unroll
;     for (int dd = 0; dd < 2; ++dd)
; #pragma unroll
;       for (int r = 0; r < 16; ++r) o[dd][r] = 0.f;
;     bf16x8 qr[6];
;     {
;       const bf16_t* Qw = Qg + qrow * 1536 + h * 96 + hi * 8;
; #pragma unroll
;       for (int d0 = 0; d0 < 6; ++d0) qr[d0] = *(const bf16x8*)(Qw + d0 * 16);
;       const int t = qblk * 256 + wid * 32 + r32;
;       const f32x2* tb = rope + (hi ? (t & 63) : (t >> 6)) * 8;
;       const u32x4 x1 = *(const u32x4*)&qr[4], x2 = *(const u32x4*)&qr[5];
;       u32x4 n1, n2;
; #pragma unroll
;       for (int q = 0; q < 4; ++q) {
;         const f32x2 csA = tb[2 * q], csB = tb[2 * q + 1];
;         const float a0 = lo16(x1[q]), a1 = hi16(x1[q]), b0 = lo16(x2[q]), b1 = hi16(x2[q]);
;         n1[q] = cvtpk(a0 * csA[0] - b0 * csA[1], a1 * csB[0] - b1 * csB[1]);
;         n2[q] = cvtpk(a0 * csA[1] + b0 * csA[0], a1 * csB[1] + b1 * csB[0]);
;       }
;       qr[4] = *(bf16x8*)&n1; qr[5] = *(bf16x8*)&n2;
;     }
;     struct { bf16x8 vs, ks, ps; } sr_[2];
;     ...
;     f32x16 pA0, pA1, pB0, pB1; float alA, alB; bf16x8 pa0, pa1, pa2, pa3;
;     constexpr int NT = TL / 64;
;     SLOAD(0, 0); asm volatile("s_waitcnt vmcnt(0)" ::: "memory"); SWRITE(0, 0); __syncthreads();
;     at_qkt(pA0, pA1, K_lds, qr, r32, hi, 0.f); at_partialSM(pA0, pA1, m_reg, alA, true);
;     SLOAD(1, 64); SLOAD(0, 128);
;     SWAIT(); SWRITE(1, 1); __syncthreads();
.Lat_kd1:
	v_add_co_u32_e32 v250, vcc, v252, v250
	v_addc_co_u32_e32 v251, vcc, 0, v251, vcc
	s_add_i32 m0, s41, 0x13400
	s_cmp_lt_u32 s14, 5
	global_load_lds_dwordx4 v[246:247], off
	v_add_co_u32_e32 v246, vcc, v248, v246
	v_addc_co_u32_e32 v247, vcc, 0, v247, vcc
	s_cbranch_scc0 .Lat_kd2
	s_add_i32 m0, s30, 0x13400
	s_nop 0
	global_load_lds_dwordx4 v[250:251], off
.Lat_kd2:
	v_add_co_u32_e32 v250, vcc, v252, v250
	v_addc_co_u32_e32 v251, vcc, 0, v251, vcc
	s_add_i32 m0, s41, 0x16800
	s_cmp_lt_u32 s14, 5
	global_load_lds_dwordx4 v[246:247], off
	v_add_co_u32_e32 v246, vcc, v248, v246
	v_addc_co_u32_e32 v247, vcc, 0, v247, vcc
	s_cbranch_scc0 .Lat_kd3
	s_add_i32 m0, s30, 0x16800
	s_nop 0
	global_load_lds_dwordx4 v[250:251], off
.Lat_kd3:
	v_add_co_u32_e32 v250, vcc, v252, v250
	v_addc_co_u32_e32 v251, vcc, 0, v251, vcc
	s_add_i32 m0, s40, 0x0
	s_nop 0
	global_load_lds_dwordx4 v131, s[36:37]
	s_add_u32 s36, s36, 0x40000
	s_addc_u32 s37, s37, 0
	s_add_i32 m0, s40, 0x4000
	s_nop 0
	global_load_lds_dwordx4 v131, s[36:37]
	s_add_u32 s36, s36, 0x40000
	s_addc_u32 s37, s37, 0
	s_waitcnt vmcnt(0)
	v_lshlrev_b32_e32 v175, 16, v96
	v_and_b32_e32 v183, 0xffff0000, v96
	v_lshlrev_b32_e32 v228, 16, v100
	v_and_b32_e32 v229, 0xffff0000, v100
	v_mul_f32_e32 v230, v228, v33
	v_mul_f32_e32 v174, v229, v35
	v_fma_f32 v230, v175, v32, -v230
	v_fma_f32 v174, v183, v34, -v174
	v_mul_f32_e32 v175, v175, v33
	v_mul_f32_e32 v183, v183, v35
	v_fma_f32 v175, v228, v32, v175
	v_fma_f32 v183, v229, v34, v183
	v_cvt_pk_bf16_f32 v96, v230, v174
	v_cvt_pk_bf16_f32 v100, v175, v183
	v_lshlrev_b32_e32 v175, 16, v97
	v_and_b32_e32 v183, 0xffff0000, v97
	v_lshlrev_b32_e32 v228, 16, v101
	v_and_b32_e32 v229, 0xffff0000, v101
	v_mul_f32_e32 v230, v228, v37
	v_mul_f32_e32 v174, v229, v39
	v_fma_f32 v230, v175, v36, -v230
	v_fma_f32 v174, v183, v38, -v174
	v_mul_f32_e32 v175, v175, v37
	v_mul_f32_e32 v183, v183, v39
	v_fma_f32 v175, v228, v36, v175
	v_fma_f32 v183, v229, v38, v183
	v_cvt_pk_bf16_f32 v97, v230, v174
	v_cvt_pk_bf16_f32 v101, v175, v183
	v_lshlrev_b32_e32 v175, 16, v98
	v_and_b32_e32 v183, 0xffff0000, v98
	v_lshlrev_b32_e32 v228, 16, v102
	v_and_b32_e32 v229, 0xffff0000, v102
	v_mul_f32_e32 v230, v228, v41
	v_mul_f32_e32 v174, v229, v43
	v_fma_f32 v230, v175, v40, -v230
	v_fma_f32 v174, v183, v42, -v174
	v_mul_f32_e32 v175, v175, v41
	v_mul_f32_e32 v183, v183, v43
	v_fma_f32 v175, v228, v40, v175
	v_fma_f32 v183, v229, v42, v183
	v_cvt_pk_bf16_f32 v98, v230, v174
	v_cvt_pk_bf16_f32 v102, v175, v183
	v_lshlrev_b32_e32 v175, 16, v99
	v_and_b32_e32 v183, 0xffff0000, v99
	v_lshlrev_b32_e32 v228, 16, v103
	v_and_b32_e32 v229, 0xffff0000, v103
	v_mul_f32_e32 v230, v228, v45
	v_mul_f32_e32 v174, v229, v47
	v_fma_f32 v230, v175, v44, -v230
	v_fma_f32 v174, v183, v46, -v174
	v_mul_f32_e32 v175, v175, v45
	v_mul_f32_e32 v183, v183, v47
	v_fma_f32 v175, v228, v44, v175
	v_fma_f32 v183, v229, v46, v183
	v_cvt_pk_bf16_f32 v99, v230, v174
	v_cvt_pk_bf16_f32 v103, v175, v183
	v_mov_b32_e32 v0, 0
	v_mov_b32_e32 v1, 0
	v_mov_b32_e32 v2, 0
	v_mov_b32_e32 v3, 0
	v_mov_b32_e32 v4, 0
	v_mov_b32_e32 v5, 0
	v_mov_b32_e32 v6, 0
	v_mov_b32_e32 v7, 0
	v_mov_b32_e32 v8, 0
	v_mov_b32_e32 v9, 0
	v_mov_b32_e32 v10, 0
	v_mov_b32_e32 v11, 0
	v_mov_b32_e32 v12, 0
	v_mov_b32_e32 v13, 0
	v_mov_b32_e32 v14, 0
	v_mov_b32_e32 v15, 0
	v_mov_b32_e32 v16, 0
	v_mov_b32_e32 v17, 0
	v_mov_b32_e32 v18, 0
	v_mov_b32_e32 v19, 0
	v_mov_b32_e32 v20, 0
	v_mov_b32_e32 v21, 0
	v_mov_b32_e32 v22, 0
	v_mov_b32_e32 v23, 0
	v_mov_b32_e32 v24, 0
	v_mov_b32_e32 v25, 0
	v_mov_b32_e32 v26, 0
	v_mov_b32_e32 v27, 0
	v_mov_b32_e32 v28, 0
	v_mov_b32_e32 v29, 0
	v_mov_b32_e32 v30, 0
	v_mov_b32_e32 v31, 0
	v_mov_b32_e32 v173, 0
	s_barrier
	ds_read_b128 v[184:187], v170 offset:0
	ds_read_b128 v[188:191], v170 offset:6656
	ds_read_b128 v[192:195], v170 offset:32
	ds_read_b128 v[196:199], v170 offset:6688
	s_cmp_eq_u32 s15, 0
	s_cbranch_scc1 .Lat_nostag
	s_barrier
.Lat_nostag:
	ds_read_b128 v[200:203], v170 offset:64
	ds_read_b128 v[204:207], v170 offset:6720
	s_waitcnt lgkmcnt(4)
	v_mfma_f32_32x32x16_bf16 v[32:47], v[184:187], v[80:83], 0
	v_mfma_f32_32x32x16_bf16 v[48:63], v[188:191], v[80:83], 0
	ds_read_b128 v[208:211], v170 offset:96
	ds_read_b128 v[212:215], v170 offset:6752
	s_waitcnt lgkmcnt(4)
	v_mfma_f32_32x32x16_bf16 v[32:47], v[192:195], v[84:87], v[32:47]
	v_mfma_f32_32x32x16_bf16 v[48:63], v[196:199], v[84:87], v[48:63]
	ds_read_b128 v[184:187], v170 offset:128
	ds_read_b128 v[188:191], v170 offset:6784
	s_waitcnt lgkmcnt(4)
	v_mfma_f32_32x32x16_bf16 v[32:47], v[200:203], v[88:91], v[32:47]
	v_mfma_f32_32x32x16_bf16 v[48:63], v[204:207], v[88:91], v[48:63]
	ds_read_b128 v[192:195], v170 offset:160
	ds_read_b128 v[196:199], v170 offset:6816
	s_waitcnt lgkmcnt(4)
	v_mfma_f32_32x32x16_bf16 v[32:47], v[208:211], v[92:95], v[32:47]
	v_mfma_f32_32x32x16_bf16 v[48:63], v[212:215], v[92:95], v[48:63]
	s_waitcnt lgkmcnt(2)
	v_mfma_f32_32x32x16_bf16 v[32:47], v[184:187], v[96:99], v[32:47]
	v_mfma_f32_32x32x16_bf16 v[48:63], v[188:191], v[96:99], v[48:63]
	s_waitcnt lgkmcnt(0)
	v_mfma_f32_32x32x16_bf16 v[32:47], v[192:195], v[100:103], v[32:47]
	v_mfma_f32_32x32x16_bf16 v[48:63], v[196:199], v[100:103], v[48:63]
	s_nop 11
	v_max3_f32 v174, v32, v33, v34
	v_max3_f32 v175, v48, v49, v50
	v_max3_f32 v174, v174, v35, v36
	v_max3_f32 v175, v175, v51, v52
	v_max3_f32 v174, v174, v37, v38
	v_max3_f32 v175, v175, v53, v54
	v_max3_f32 v174, v174, v39, v40
	v_max3_f32 v175, v175, v55, v56
	v_max3_f32 v174, v174, v41, v42
	v_max3_f32 v175, v175, v57, v58
	v_max3_f32 v174, v174, v43, v44
	v_max3_f32 v175, v175, v59, v60
	v_max3_f32 v174, v174, v45, v46
	v_max3_f32 v175, v175, v61, v62
	v_max3_f32 v174, v174, v47, v63
	v_max_f32_e32 v174, v174, v175
	v_mov_b32_e32 v175, v174
	s_nop 1
	v_permlane32_swap_b32_e32 v174, v175
	v_max_f32_e32 v174, v174, v175
	s_barrier
; #define SBAR() __builtin_amdgcn_sched_barrier(0)
; #define SLOAD(i, k0) do { sr_[i].vs = *(const bf16x8*)(Kh + (size_t)((k0) + skey) * 2048 + 64 + sc8); \
;     sr_[i].ks = *(const bf16x8*)(Kh + (size_t)((k0) + skey) * 2048 + sc8); \
;     sr_[i].ps = *(const bf16x8*)(Kp + (size_t)((k0) + pkey) * 32 + pc8); } while (0)
; #define SWRITE(bb, i) do { *(bf16x8*)(V_lds + (bb) * AT_SHMV + vst) = sr_[i].vs; \
;     *(bf16x8*)(K_lds + (bb) * AT_SHMK + kst) = sr_[i].ks; \
;     *(bf16x8*)(K_lds + (bb) * AT_SHMK + pst) = sr_[i].ps; } while (0)
; #define SWAIT() asm volatile("s_waitcnt vmcnt(3)" ::: "memory")
; __device__ __forceinline__ void at_partialSM(f32x16& p0, f32x16& p1, float& m_reg, float& alpha, bool force) {
;     ...
;   if (__builtin_expect(!force && __all(pm <= AT_THR * 1.4426950408889634f), 1)) { alpha = 1.f; }
;   else {
;     const float dlt = force ? pm : fmaxf(pm, 0.f);
;     alpha = force ? 1.f : __builtin_amdgcn_exp2f(-dlt); m_reg += dlt;
; #pragma unroll
;     for (int r = 0; r < 16; ++r) { p0[r] -= dlt; p1[r] -= dlt; }
;   }
; #pragma unroll
;   for (int r = 0; r < 16; ++r) p0[r] = __builtin_amdgcn_exp2f(p0[r]);
; }
; __device__ __forceinline__ void at_finishSM(f32x16& p0, f32x16& p1, float alpha, float& l_reg, bf16x8& pa0, bf16x8& pa1, bf16x8& pa2, bf16x8& pa3) {
; #pragma unroll
;   for (int r = 0; r < 16; ++r) p1[r] = __builtin_amdgcn_exp2f(p1[r]);
;   float ps = 0;
; #pragma unroll
;   for (int r = 0; r < 16; ++r) ps += p0[r];
; #pragma unroll
;   for (int r = 0; r < 16; ++r) ps += p1[r];
;   { auto rr = __builtin_amdgcn_permlane32_swap(__float_as_uint(ps), __float_as_uint(ps), false, false);
;     ps = __uint_as_float(rr[0]) + __uint_as_float(rr[1]); }
;   l_reg = l_reg * alpha + ps;
;     ...
;   PK4(p0, 0, pa0); PK4(p0, 8, pa1); PK4(p1, 0, pa2); PK4(p1, 8, pa3);
; __device__ void phase_attn(const Params& p, char* lds) {
;     ...
;     SLOAD(0, 0); asm volatile("s_waitcnt vmcnt(0)" ::: "memory"); SWRITE(0, 0); __syncthreads();
;     at_qkt(pA0, pA1, K_lds, qr, r32, hi, 0.f); at_partialSM(pA0, pA1, m_reg, alA, true);
;     SLOAD(1, 64); SLOAD(0, 128);
;     SWAIT(); SWRITE(1, 1); __syncthreads();
;     for (int j = 1; j + 1 < NT; j += 2) {
;       SBAR(); at_qkt(pB0, pB1, K_lds + AT_SHMK, qr, r32, hi, -m_reg);
;       at_finishSM(pA0, pA1, alA, l_reg, pa0, pa1, pa2, pa3); SBAR();
;       SLOAD(1, (j + 2) * 64); SBAR();
	v_mov_b32_e32 v172, v174
	v_sub_f32_e32 v32, v32, v174
	v_sub_f32_e32 v48, v48, v174
	v_sub_f32_e32 v33, v33, v174
	v_sub_f32_e32 v49, v49, v174
	v_sub_f32_e32 v34, v34, v174
	v_sub_f32_e32 v50, v50, v174
	v_sub_f32_e32 v35, v35, v174
	v_sub_f32_e32 v51, v51, v174
	v_sub_f32_e32 v36, v36, v174
	v_sub_f32_e32 v52, v52, v174
	v_sub_f32_e32 v37, v37, v174
	v_sub_f32_e32 v53, v53, v174
	v_sub_f32_e32 v38, v38, v174
	v_sub_f32_e32 v54, v54, v174
	v_sub_f32_e32 v39, v39, v174
	v_sub_f32_e32 v55, v55, v174
	v_sub_f32_e32 v40, v40, v174
	v_sub_f32_e32 v56, v56, v174
	v_sub_f32_e32 v41, v41, v174
	v_sub_f32_e32 v57, v57, v174
	v_sub_f32_e32 v42, v42, v174
	v_sub_f32_e32 v58, v58, v174
	v_sub_f32_e32 v43, v43, v174
	v_sub_f32_e32 v59, v59, v174
	v_sub_f32_e32 v44, v44, v174
	v_sub_f32_e32 v60, v60, v174
	v_sub_f32_e32 v45, v45, v174
	v_sub_f32_e32 v61, v61, v174
	v_sub_f32_e32 v46, v46, v174
	v_sub_f32_e32 v62, v62, v174
	v_sub_f32_e32 v47, v47, v174
	v_sub_f32_e32 v63, v63, v174
	v_sub_f32_e32 v64, 0, v174
	v_sub_f32_e32 v65, 0, v174
	v_sub_f32_e32 v66, 0, v174
	v_sub_f32_e32 v67, 0, v174
	v_sub_f32_e32 v68, 0, v174
	v_sub_f32_e32 v69, 0, v174
	v_sub_f32_e32 v70, 0, v174
	v_sub_f32_e32 v71, 0, v174
	v_sub_f32_e32 v72, 0, v174
	v_sub_f32_e32 v73, 0, v174
	v_sub_f32_e32 v74, 0, v174
	v_sub_f32_e32 v75, 0, v174
	v_sub_f32_e32 v76, 0, v174
	v_sub_f32_e32 v77, 0, v174
	v_sub_f32_e32 v78, 0, v174
	v_sub_f32_e32 v79, 0, v174
	s_add_i32 m0, s41, 0x19c00
	s_cmp_lt_u32 s14, 5
	global_load_lds_dwordx4 v[246:247], off
	v_add_co_u32_e32 v246, vcc, v248, v246
	v_addc_co_u32_e32 v247, vcc, 0, v247, vcc
	s_cbranch_scc0 .Lat_kd4
	s_add_i32 m0, s30, 0x19c00
	s_nop 0
	global_load_lds_dwordx4 v[250:251], off
.Lat_kd4:
	v_add_co_u32_e32 v250, vcc, v252, v250
	v_addc_co_u32_e32 v251, vcc, 0, v251, vcc
	s_add_i32 m0, s40, 0x8000
	s_nop 0
	global_load_lds_dwordx4 v131, s[36:37]
	s_add_u32 s36, s36, 0x40000
	s_addc_u32 s37, s37, 0
	v_exp_f32_e32 v32, v32
	v_exp_f32_e32 v48, v48
	v_exp_f32_e32 v33, v33
	v_exp_f32_e32 v49, v49
	v_exp_f32_e32 v34, v34
	v_exp_f32_e32 v50, v50
	v_exp_f32_e32 v35, v35
	v_exp_f32_e32 v51, v51
	v_exp_f32_e32 v36, v36
	v_exp_f32_e32 v52, v52
	v_exp_f32_e32 v37, v37
	v_exp_f32_e32 v53, v53
	v_exp_f32_e32 v38, v38
	v_exp_f32_e32 v54, v54
	v_exp_f32_e32 v39, v39
	v_exp_f32_e32 v55, v55
	v_exp_f32_e32 v40, v40
	v_exp_f32_e32 v56, v56
	v_exp_f32_e32 v41, v41
	v_exp_f32_e32 v57, v57
	v_exp_f32_e32 v42, v42
	v_exp_f32_e32 v58, v58
	v_exp_f32_e32 v43, v43
	v_exp_f32_e32 v59, v59
	v_exp_f32_e32 v44, v44
	v_exp_f32_e32 v60, v60
	v_exp_f32_e32 v45, v45
	v_exp_f32_e32 v61, v61
	v_exp_f32_e32 v46, v46
	v_exp_f32_e32 v62, v62
	v_exp_f32_e32 v47, v47
	v_exp_f32_e32 v63, v63
	v_add_f32_e32 v175, v32, v33
	v_add_f32_e32 v174, v48, v49
	v_add_f32_e32 v175, v175, v34
	v_add_f32_e32 v174, v174, v50
	v_add_f32_e32 v175, v175, v35
	v_add_f32_e32 v174, v174, v51
	v_add_f32_e32 v175, v175, v36
	v_add_f32_e32 v174, v174, v52
	v_add_f32_e32 v175, v175, v37
	v_add_f32_e32 v174, v174, v53
	v_add_f32_e32 v175, v175, v38
	v_add_f32_e32 v174, v174, v54
	v_add_f32_e32 v175, v175, v39
	v_add_f32_e32 v174, v174, v55
	v_add_f32_e32 v175, v175, v40
	v_add_f32_e32 v174, v174, v56
	v_add_f32_e32 v175, v175, v41
	v_add_f32_e32 v174, v174, v57
	v_add_f32_e32 v175, v175, v42
	v_add_f32_e32 v174, v174, v58
	v_add_f32_e32 v175, v175, v43
	v_add_f32_e32 v174, v174, v59
	v_add_f32_e32 v175, v175, v44
	v_add_f32_e32 v174, v174, v60
	v_add_f32_e32 v175, v175, v45
	v_add_f32_e32 v174, v174, v61
	v_add_f32_e32 v175, v175, v46
	v_add_f32_e32 v174, v174, v62
	v_add_f32_e32 v175, v175, v47
	v_add_f32_e32 v174, v174, v63
	v_add_f32_e32 v175, v175, v174
	v_add_f32_e32 v173, v173, v175
	v_cvt_pk_bf16_f32 v104, v32, v33
	v_cvt_pk_bf16_f32 v105, v34, v35
	v_cvt_pk_bf16_f32 v106, v36, v37
	v_cvt_pk_bf16_f32 v107, v38, v39
	v_cvt_pk_bf16_f32 v108, v40, v41
	v_cvt_pk_bf16_f32 v109, v42, v43
	v_cvt_pk_bf16_f32 v110, v44, v45
	v_cvt_pk_bf16_f32 v111, v46, v47
	v_cvt_pk_bf16_f32 v112, v48, v49
	v_cvt_pk_bf16_f32 v113, v50, v51
	v_cvt_pk_bf16_f32 v114, v52, v53
	v_cvt_pk_bf16_f32 v115, v54, v55
	v_cvt_pk_bf16_f32 v116, v56, v57
	v_cvt_pk_bf16_f32 v117, v58, v59
	v_cvt_pk_bf16_f32 v118, v60, v61
	v_cvt_pk_bf16_f32 v119, v62, v63
	ds_read_b128 v[184:187], v170 offset:13312
	ds_read_b128 v[188:191], v170 offset:19968
	ds_read_b128 v[192:195], v170 offset:13344
	ds_read_b128 v[196:199], v170 offset:20000
	s_barrier
	s_mov_b32 s13, 32
; #define MFMA(a, b, c) __builtin_amdgcn_mfma_f32_32x32x16_bf16((a), (b), (c), 0, 0, 0)
; #define SBAR() __builtin_amdgcn_sched_barrier(0)
; #define SWAIT() asm volatile("s_waitcnt vmcnt(3)" ::: "memory")
; __device__ __forceinline__ void at_qkt(f32x16& p0, f32x16& p1, const char* Ks, const bf16x8* qr, int r32, int hi, float negm) {
; #pragma unroll
;   for (int r = 0; r < 16; ++r) { p0[r] = negm; p1[r] = negm; }
; #pragma unroll
;   for (int d0 = 0; d0 < 6; ++d0) {
;     const bf16x8 b0 = *(const bf16x8*)(Ks + r32 * AT_KROW + d0 * 32 + hi * 16);
;     const bf16x8 b1 = *(const bf16x8*)(Ks + (32 + r32) * AT_KROW + d0 * 32 + hi * 16);
;     p0 = MFMA(b0, qr[d0], p0);
;     p1 = MFMA(b1, qr[d0], p1);
;   }
; }
; __device__ __forceinline__ int v_st(int k, int c) { const int kk = (k & ~0xC) | ((k & 4) << 1) | ((k & 8) >> 1); return ((kk >> 3) * 4 + (c >> 5)) * 512 + ((kk & 7) * 32 + (c & 31)) * 2; }
; __device__ __forceinline__ int v_rd_base(int lane) { return ((lane & 3) << 3) | (((lane >> 2) & 3) << 6) | (((lane >> 4) & 1) << 5) | (((lane >> 5) & 1) << 8); }
; template <int OFF> __device__ __forceinline__ s16x4 tr_read(int vb) {
;   s16x4 r; asm volatile("ds_read_b64_tr_b16 %0, %1 offset:%2" : "=&v"(r) : "v"(vb), "i"(OFF) : "memory"); return r;
; }
; template <int D0> __device__ __forceinline__ void pv_one(f32x16& od, int vb, bf16x8 pa0, bf16x8 pa1, bf16x8 pa2, bf16x8 pa3) {
;   const s16x4 l0 = tr_read<v_rd_off(D0, 0, 0)>(vb), h0 = tr_read<v_rd_off(D0, 0, 1)>(vb), l1 = tr_read<v_rd_off(D0, 1, 0)>(vb), h1 = tr_read<v_rd_off(D0, 1, 1)>(vb);
;   const s16x4 l2 = tr_read<v_rd_off(D0, 2, 0)>(vb), h2 = tr_read<v_rd_off(D0, 2, 1)>(vb), l3 = tr_read<v_rd_off(D0, 3, 0)>(vb), h3 = tr_read<v_rd_off(D0, 3, 1)>(vb);
;   asm volatile("s_waitcnt lgkmcnt(0)" ::: "memory"); SBAR();
;     ...
;   od = MFMA(pa0, PK(l0, h0), od);
;   od = MFMA(pa1, PK(l1, h1), od);
;   od = MFMA(pa2, PK(l2, h2), od);
;   od = MFMA(pa3, PK(l3, h3), od);
;     ...
; }
; __device__ void phase_attn(const Params& p, char* lds) {
;     ...
;     for (int j = 1; j + 1 < NT; j += 2) {
;       SBAR(); at_qkt(pB0, pB1, K_lds + AT_SHMK, qr, r32, hi, -m_reg);
;       at_finishSM(pA0, pA1, alA, l_reg, pa0, pa1, pa2, pa3); SBAR();
;       SLOAD(1, (j + 2) * 64); SBAR();
;       pv_d0(o, vb0, pa0, pa1, pa2, pa3); at_partialSM(pB0, pB1, m_reg, alB, false);
;       __syncthreads(); SWAIT(); SWRITE(0, 0);
;       RESC(alB); __syncthreads();
.Lat_loop:
	ds_read_b128 v[200:203], v170 offset:13376
	ds_read_b128 v[204:207], v170 offset:20032
	s_waitcnt lgkmcnt(4)
	v_mfma_f32_32x32x16_bf16 v[32:47], v[184:187], v[80:83], v[64:79]
	v_mfma_f32_32x32x16_bf16 v[48:63], v[188:191], v[80:83], v[64:79]
	ds_read_b128 v[208:211], v170 offset:13408
	ds_read_b128 v[212:215], v170 offset:20064
	s_waitcnt lgkmcnt(4)
	v_mfma_f32_32x32x16_bf16 v[32:47], v[192:195], v[84:87], v[32:47]
	v_mfma_f32_32x32x16_bf16 v[48:63], v[196:199], v[84:87], v[48:63]
	ds_read_b128 v[184:187], v170 offset:13440
	ds_read_b128 v[188:191], v170 offset:20096
	s_waitcnt lgkmcnt(4)
	v_mfma_f32_32x32x16_bf16 v[32:47], v[200:203], v[88:91], v[32:47]
	v_mfma_f32_32x32x16_bf16 v[48:63], v[204:207], v[88:91], v[48:63]
	ds_read_b128 v[192:195], v170 offset:13472
	ds_read_b128 v[196:199], v170 offset:20128
	s_waitcnt lgkmcnt(4)
	v_mfma_f32_32x32x16_bf16 v[32:47], v[208:211], v[92:95], v[32:47]
	v_mfma_f32_32x32x16_bf16 v[48:63], v[212:215], v[92:95], v[48:63]
	ds_read_b64_tr_b16 v[148:149], v171 offset:0
	ds_read_b64_tr_b16 v[150:151], v171 offset:2048
	ds_read_b64_tr_b16 v[152:153], v171 offset:4096
	ds_read_b64_tr_b16 v[154:155], v171 offset:6144
	s_waitcnt lgkmcnt(6)
	v_mfma_f32_32x32x16_bf16 v[32:47], v[184:187], v[96:99], v[32:47]
	v_mfma_f32_32x32x16_bf16 v[48:63], v[188:191], v[96:99], v[48:63]
	ds_read_b64_tr_b16 v[156:157], v171 offset:8192
	ds_read_b64_tr_b16 v[158:159], v171 offset:10240
	ds_read_b64_tr_b16 v[216:217], v171 offset:12288
	ds_read_b64_tr_b16 v[218:219], v171 offset:14336
	s_waitcnt lgkmcnt(8)
	v_mfma_f32_32x32x16_bf16 v[32:47], v[192:195], v[100:103], v[32:47]
	v_mfma_f32_32x32x16_bf16 v[48:63], v[196:199], v[100:103], v[48:63]
	ds_read_b64_tr_b16 v[220:221], v171 offset:512
	ds_read_b64_tr_b16 v[222:223], v171 offset:2560
	ds_read_b64_tr_b16 v[224:225], v171 offset:4608
	ds_read_b64_tr_b16 v[226:227], v171 offset:6656
	s_waitcnt lgkmcnt(10)
	v_mfma_f32_32x32x16_bf16 v[0:15], v[104:107], v[148:151], v[0:15]
	s_waitcnt lgkmcnt(8)
	v_mfma_f32_32x32x16_bf16 v[0:15], v[108:111], v[152:155], v[0:15]
	ds_read_b64_tr_b16 v[236:237], v171 offset:8704
	ds_read_b64_tr_b16 v[238:239], v171 offset:10752
	ds_read_b64_tr_b16 v[240:241], v171 offset:12800
	ds_read_b64_tr_b16 v[242:243], v171 offset:14848
	s_waitcnt lgkmcnt(10)
	v_mfma_f32_32x32x16_bf16 v[0:15], v[112:115], v[156:159], v[0:15]
	s_waitcnt lgkmcnt(8)
	v_mfma_f32_32x32x16_bf16 v[0:15], v[116:119], v[216:219], v[0:15]
	s_waitcnt lgkmcnt(6)
	v_mfma_f32_32x32x16_bf16 v[16:31], v[104:107], v[220:223], v[16:31]
	s_waitcnt lgkmcnt(4)
	v_mfma_f32_32x32x16_bf16 v[16:31], v[108:111], v[224:227], v[16:31]
	s_waitcnt lgkmcnt(2)
	v_mfma_f32_32x32x16_bf16 v[16:31], v[112:115], v[236:239], v[16:31]
	s_waitcnt lgkmcnt(0)
	v_mfma_f32_32x32x16_bf16 v[16:31], v[116:119], v[240:243], v[16:31]
	s_barrier
	s_waitcnt vmcnt(0)
	s_add_i32 m0, s41, 0x10000
	s_cmp_lt_u32 s14, 5
	global_load_lds_dwordx4 v[246:247], off
	v_add_co_u32_e32 v246, vcc, v248, v246
	v_addc_co_u32_e32 v247, vcc, 0, v247, vcc
	s_cbranch_scc0 .Lat_kd5
	s_add_i32 m0, s30, 0x10000
	s_nop 0
	global_load_lds_dwordx4 v[250:251], off
.Lat_kd5:
	v_add_co_u32_e32 v250, vcc, v252, v250
	v_addc_co_u32_e32 v251, vcc, 0, v251, vcc
	s_add_i32 m0, s40, 0xc000
	s_nop 0
	global_load_lds_dwordx4 v131, s[36:37]
	s_add_u32 s36, s36, 0x40000
	s_addc_u32 s37, s37, 0
	v_exp_f32_e32 v32, v32
	v_exp_f32_e32 v48, v48
	v_exp_f32_e32 v33, v33
	v_exp_f32_e32 v49, v49
	v_exp_f32_e32 v34, v34
	v_exp_f32_e32 v50, v50
	v_exp_f32_e32 v35, v35
	v_exp_f32_e32 v51, v51
	v_exp_f32_e32 v36, v36
	v_exp_f32_e32 v52, v52
	v_exp_f32_e32 v37, v37
	v_exp_f32_e32 v53, v53
	v_exp_f32_e32 v38, v38
	v_exp_f32_e32 v54, v54
	v_exp_f32_e32 v39, v39
	v_exp_f32_e32 v55, v55
	v_exp_f32_e32 v40, v40
	v_exp_f32_e32 v56, v56
	v_exp_f32_e32 v41, v41
	v_exp_f32_e32 v57, v57
	v_exp_f32_e32 v42, v42
	v_exp_f32_e32 v58, v58
	v_exp_f32_e32 v43, v43
	v_exp_f32_e32 v59, v59
	v_exp_f32_e32 v44, v44
	v_exp_f32_e32 v60, v60
	v_exp_f32_e32 v45, v45
	v_exp_f32_e32 v61, v61
	v_exp_f32_e32 v46, v46
	v_exp_f32_e32 v62, v62
	v_exp_f32_e32 v47, v47
	v_exp_f32_e32 v63, v63
	v_add_f32_e32 v175, v32, v33
	v_add_f32_e32 v174, v48, v49
	v_add_f32_e32 v175, v175, v34
	v_add_f32_e32 v174, v174, v50
	v_add_f32_e32 v175, v175, v35
	v_add_f32_e32 v174, v174, v51
	v_add_f32_e32 v175, v175, v36
	v_add_f32_e32 v174, v174, v52
	v_add_f32_e32 v175, v175, v37
	v_add_f32_e32 v174, v174, v53
	v_add_f32_e32 v175, v175, v38
	v_add_f32_e32 v174, v174, v54
	v_add_f32_e32 v175, v175, v39
	v_add_f32_e32 v174, v174, v55
	v_add_f32_e32 v175, v175, v40
	v_add_f32_e32 v174, v174, v56
	v_add_f32_e32 v175, v175, v41
	v_add_f32_e32 v174, v174, v57
	v_add_f32_e32 v175, v175, v42
	v_add_f32_e32 v174, v174, v58
	v_add_f32_e32 v175, v175, v43
	v_add_f32_e32 v174, v174, v59
	v_add_f32_e32 v175, v175, v44
	v_add_f32_e32 v174, v174, v60
	v_add_f32_e32 v175, v175, v45
	v_add_f32_e32 v174, v174, v61
	v_add_f32_e32 v175, v175, v46
	v_add_f32_e32 v174, v174, v62
	v_add_f32_e32 v175, v175, v47
	v_add_f32_e32 v174, v174, v63
	v_add_f32_e32 v175, v175, v174
	v_cmp_ge_f32_e32 vcc, s23, v175
	s_cmp_eq_u64 vcc, exec
	s_cbranch_scc0 .Lat_rare0
; #define MFMA(a, b, c) __builtin_amdgcn_mfma_f32_32x32x16_bf16((a), (b), (c), 0, 0, 0)
; #define SBAR() __builtin_amdgcn_sched_barrier(0)
; #define SWAIT() asm volatile("s_waitcnt vmcnt(3)" ::: "memory")
; __device__ __forceinline__ void at_qkt(f32x16& p0, f32x16& p1, const char* Ks, const bf16x8* qr, int r32, int hi, float negm) {
; #pragma unroll
;   for (int r = 0; r < 16; ++r) { p0[r] = negm; p1[r] = negm; }
; #pragma unroll
;   for (int d0 = 0; d0 < 6; ++d0) {
;     const bf16x8 b0 = *(const bf16x8*)(Ks + r32 * AT_KROW + d0 * 32 + hi * 16);
;     const bf16x8 b1 = *(const bf16x8*)(Ks + (32 + r32) * AT_KROW + d0 * 32 + hi * 16);
;     p0 = MFMA(b0, qr[d0], p0);
;     p1 = MFMA(b1, qr[d0], p1);
;   }
; }
; __device__ __forceinline__ int v_st(int k, int c) { const int kk = (k & ~0xC) | ((k & 4) << 1) | ((k & 8) >> 1); return ((kk >> 3) * 4 + (c >> 5)) * 512 + ((kk & 7) * 32 + (c & 31)) * 2; }
; __device__ __forceinline__ int v_rd_base(int lane) { return ((lane & 3) << 3) | (((lane >> 2) & 3) << 6) | (((lane >> 4) & 1) << 5) | (((lane >> 5) & 1) << 8); }
; template <int OFF> __device__ __forceinline__ s16x4 tr_read(int vb) {
;   s16x4 r; asm volatile("ds_read_b64_tr_b16 %0, %1 offset:%2" : "=&v"(r) : "v"(vb), "i"(OFF) : "memory"); return r;
; }
; template <int D0> __device__ __forceinline__ void pv_one(f32x16& od, int vb, bf16x8 pa0, bf16x8 pa1, bf16x8 pa2, bf16x8 pa3) {
;   const s16x4 l0 = tr_read<v_rd_off(D0, 0, 0)>(vb), h0 = tr_read<v_rd_off(D0, 0, 1)>(vb), l1 = tr_read<v_rd_off(D0, 1, 0)>(vb), h1 = tr_read<v_rd_off(D0, 1, 1)>(vb);
;   const s16x4 l2 = tr_read<v_rd_off(D0, 2, 0)>(vb), h2 = tr_read<v_rd_off(D0, 2, 1)>(vb), l3 = tr_read<v_rd_off(D0, 3, 0)>(vb), h3 = tr_read<v_rd_off(D0, 3, 1)>(vb);
;   asm volatile("s_waitcnt lgkmcnt(0)" ::: "memory"); SBAR();
;     ...
;   od = MFMA(pa0, PK(l0, h0), od);
;   od = MFMA(pa1, PK(l1, h1), od);
;   od = MFMA(pa2, PK(l2, h2), od);
;   od = MFMA(pa3, PK(l3, h3), od);
;     ...
; }
; __device__ void phase_attn(const Params& p, char* lds) {
;     ...
;       SBAR(); at_qkt(pA0, pA1, K_lds, qr, r32, hi, -m_reg);
;       at_finishSM(pB0, pB1, alB, l_reg, pa0, pa1, pa2, pa3); SBAR();
;       if (j + 3 < NT) SLOAD(0, (j + 3) * 64); SBAR();
;       pv_d0(o, vb0 + AT_SHMV, pa0, pa1, pa2, pa3); at_partialSM(pA0, pA1, m_reg, alA, false);
;       __syncthreads(); SWAIT(); SWRITE(1, 1);
;       RESC(alA); __syncthreads();
.Lat_rare0_back:
	v_add_f32_e32 v173, v173, v175
	v_cvt_pk_bf16_f32 v104, v32, v33
	v_cvt_pk_bf16_f32 v105, v34, v35
	v_cvt_pk_bf16_f32 v106, v36, v37
	v_cvt_pk_bf16_f32 v107, v38, v39
	v_cvt_pk_bf16_f32 v108, v40, v41
	v_cvt_pk_bf16_f32 v109, v42, v43
	v_cvt_pk_bf16_f32 v110, v44, v45
	v_cvt_pk_bf16_f32 v111, v46, v47
	v_cvt_pk_bf16_f32 v112, v48, v49
	v_cvt_pk_bf16_f32 v113, v50, v51
	v_cvt_pk_bf16_f32 v114, v52, v53
	v_cvt_pk_bf16_f32 v115, v54, v55
	v_cvt_pk_bf16_f32 v116, v56, v57
	v_cvt_pk_bf16_f32 v117, v58, v59
	v_cvt_pk_bf16_f32 v118, v60, v61
	v_cvt_pk_bf16_f32 v119, v62, v63
	ds_read_b128 v[184:187], v170 offset:26624
	ds_read_b128 v[188:191], v170 offset:33280
	ds_read_b128 v[192:195], v170 offset:26656
	ds_read_b128 v[196:199], v170 offset:33312
	s_barrier
	ds_read_b128 v[200:203], v170 offset:26688
	ds_read_b128 v[204:207], v170 offset:33344
	s_waitcnt lgkmcnt(4)
	v_mfma_f32_32x32x16_bf16 v[32:47], v[184:187], v[80:83], v[64:79]
	v_mfma_f32_32x32x16_bf16 v[48:63], v[188:191], v[80:83], v[64:79]
	ds_read_b128 v[208:211], v170 offset:26720
	ds_read_b128 v[212:215], v170 offset:33376
	s_waitcnt lgkmcnt(4)
	v_mfma_f32_32x32x16_bf16 v[32:47], v[192:195], v[84:87], v[32:47]
	v_mfma_f32_32x32x16_bf16 v[48:63], v[196:199], v[84:87], v[48:63]
	ds_read_b128 v[184:187], v170 offset:26752
	ds_read_b128 v[188:191], v170 offset:33408
	s_waitcnt lgkmcnt(4)
	v_mfma_f32_32x32x16_bf16 v[32:47], v[200:203], v[88:91], v[32:47]
	v_mfma_f32_32x32x16_bf16 v[48:63], v[204:207], v[88:91], v[48:63]
	ds_read_b128 v[192:195], v170 offset:26784
	ds_read_b128 v[196:199], v170 offset:33440
	s_waitcnt lgkmcnt(4)
	v_mfma_f32_32x32x16_bf16 v[32:47], v[208:211], v[92:95], v[32:47]
	v_mfma_f32_32x32x16_bf16 v[48:63], v[212:215], v[92:95], v[48:63]
	ds_read_b64_tr_b16 v[148:149], v171 offset:16384
	ds_read_b64_tr_b16 v[150:151], v171 offset:18432
	ds_read_b64_tr_b16 v[152:153], v171 offset:20480
	ds_read_b64_tr_b16 v[154:155], v171 offset:22528
	s_waitcnt lgkmcnt(6)
	v_mfma_f32_32x32x16_bf16 v[32:47], v[184:187], v[96:99], v[32:47]
	v_mfma_f32_32x32x16_bf16 v[48:63], v[188:191], v[96:99], v[48:63]
	ds_read_b64_tr_b16 v[156:157], v171 offset:24576
	ds_read_b64_tr_b16 v[158:159], v171 offset:26624
	ds_read_b64_tr_b16 v[216:217], v171 offset:28672
	ds_read_b64_tr_b16 v[218:219], v171 offset:30720
	s_waitcnt lgkmcnt(8)
	v_mfma_f32_32x32x16_bf16 v[32:47], v[192:195], v[100:103], v[32:47]
	v_mfma_f32_32x32x16_bf16 v[48:63], v[196:199], v[100:103], v[48:63]
	ds_read_b64_tr_b16 v[220:221], v171 offset:16896
	ds_read_b64_tr_b16 v[222:223], v171 offset:18944
	ds_read_b64_tr_b16 v[224:225], v171 offset:20992
	ds_read_b64_tr_b16 v[226:227], v171 offset:23040
	s_waitcnt lgkmcnt(10)
	v_mfma_f32_32x32x16_bf16 v[0:15], v[104:107], v[148:151], v[0:15]
	s_waitcnt lgkmcnt(8)
	v_mfma_f32_32x32x16_bf16 v[0:15], v[108:111], v[152:155], v[0:15]
	ds_read_b64_tr_b16 v[236:237], v171 offset:25088
	ds_read_b64_tr_b16 v[238:239], v171 offset:27136
	ds_read_b64_tr_b16 v[240:241], v171 offset:29184
	ds_read_b64_tr_b16 v[242:243], v171 offset:31232
	s_waitcnt lgkmcnt(10)
	v_mfma_f32_32x32x16_bf16 v[0:15], v[112:115], v[156:159], v[0:15]
	s_waitcnt lgkmcnt(8)
	v_mfma_f32_32x32x16_bf16 v[0:15], v[116:119], v[216:219], v[0:15]
	s_waitcnt lgkmcnt(6)
	v_mfma_f32_32x32x16_bf16 v[16:31], v[104:107], v[220:223], v[16:31]
	s_waitcnt lgkmcnt(4)
	v_mfma_f32_32x32x16_bf16 v[16:31], v[108:111], v[224:227], v[16:31]
	s_waitcnt lgkmcnt(2)
	v_mfma_f32_32x32x16_bf16 v[16:31], v[112:115], v[236:239], v[16:31]
	s_waitcnt lgkmcnt(0)
	v_mfma_f32_32x32x16_bf16 v[16:31], v[116:119], v[240:243], v[16:31]
	s_barrier
	s_waitcnt vmcnt(0)
	s_add_i32 m0, s41, 0x13400
	s_cmp_lt_u32 s14, 5
	global_load_lds_dwordx4 v[246:247], off
	v_add_co_u32_e32 v246, vcc, v248, v246
	v_addc_co_u32_e32 v247, vcc, 0, v247, vcc
	s_cbranch_scc0 .Lat_kd6
	s_add_i32 m0, s30, 0x13400
	s_nop 0
	global_load_lds_dwordx4 v[250:251], off
.Lat_kd6:
	v_add_co_u32_e32 v250, vcc, v252, v250
	v_addc_co_u32_e32 v251, vcc, 0, v251, vcc
	s_add_i32 m0, s40, 0x0
	s_nop 0
	global_load_lds_dwordx4 v131, s[36:37]
	s_add_u32 s36, s36, 0x40000
	s_addc_u32 s37, s37, 0
	v_exp_f32_e32 v32, v32
	v_exp_f32_e32 v48, v48
	v_exp_f32_e32 v33, v33
	v_exp_f32_e32 v49, v49
	v_exp_f32_e32 v34, v34
	v_exp_f32_e32 v50, v50
	v_exp_f32_e32 v35, v35
	v_exp_f32_e32 v51, v51
	v_exp_f32_e32 v36, v36
	v_exp_f32_e32 v52, v52
	v_exp_f32_e32 v37, v37
	v_exp_f32_e32 v53, v53
	v_exp_f32_e32 v38, v38
	v_exp_f32_e32 v54, v54
	v_exp_f32_e32 v39, v39
	v_exp_f32_e32 v55, v55
	v_exp_f32_e32 v40, v40
	v_exp_f32_e32 v56, v56
	v_exp_f32_e32 v41, v41
	v_exp_f32_e32 v57, v57
	v_exp_f32_e32 v42, v42
	v_exp_f32_e32 v58, v58
	v_exp_f32_e32 v43, v43
	v_exp_f32_e32 v59, v59
	v_exp_f32_e32 v44, v44
	v_exp_f32_e32 v60, v60
	v_exp_f32_e32 v45, v45
	v_exp_f32_e32 v61, v61
	v_exp_f32_e32 v46, v46
	v_exp_f32_e32 v62, v62
	v_exp_f32_e32 v47, v47
	v_exp_f32_e32 v63, v63
	v_add_f32_e32 v175, v32, v33
	v_add_f32_e32 v174, v48, v49
	v_add_f32_e32 v175, v175, v34
	v_add_f32_e32 v174, v174, v50
	v_add_f32_e32 v175, v175, v35
	v_add_f32_e32 v174, v174, v51
	v_add_f32_e32 v175, v175, v36
	v_add_f32_e32 v174, v174, v52
	v_add_f32_e32 v175, v175, v37
	v_add_f32_e32 v174, v174, v53
	v_add_f32_e32 v175, v175, v38
	v_add_f32_e32 v174, v174, v54
	v_add_f32_e32 v175, v175, v39
	v_add_f32_e32 v174, v174, v55
	v_add_f32_e32 v175, v175, v40
	v_add_f32_e32 v174, v174, v56
	v_add_f32_e32 v175, v175, v41
	v_add_f32_e32 v174, v174, v57
	v_add_f32_e32 v175, v175, v42
	v_add_f32_e32 v174, v174, v58
	v_add_f32_e32 v175, v175, v43
	v_add_f32_e32 v174, v174, v59
	v_add_f32_e32 v175, v175, v44
	v_add_f32_e32 v174, v174, v60
	v_add_f32_e32 v175, v175, v45
	v_add_f32_e32 v174, v174, v61
	v_add_f32_e32 v175, v175, v46
	v_add_f32_e32 v174, v174, v62
	v_add_f32_e32 v175, v175, v47
	v_add_f32_e32 v174, v174, v63
	v_add_f32_e32 v175, v175, v174
	v_cmp_ge_f32_e32 vcc, s23, v175
	s_cmp_eq_u64 vcc, exec
	s_cbranch_scc0 .Lat_rare1
; #define MFMA(a, b, c) __builtin_amdgcn_mfma_f32_32x32x16_bf16((a), (b), (c), 0, 0, 0)
; #define SBAR() __builtin_amdgcn_sched_barrier(0)
; #define SWAIT() asm volatile("s_waitcnt vmcnt(3)" ::: "memory")
; __device__ __forceinline__ void at_qkt(f32x16& p0, f32x16& p1, const char* Ks, const bf16x8* qr, int r32, int hi, float negm) {
; #pragma unroll
;   for (int r = 0; r < 16; ++r) { p0[r] = negm; p1[r] = negm; }
; #pragma unroll
;   for (int d0 = 0; d0 < 6; ++d0) {
;     const bf16x8 b0 = *(const bf16x8*)(Ks + r32 * AT_KROW + d0 * 32 + hi * 16);
;     const bf16x8 b1 = *(const bf16x8*)(Ks + (32 + r32) * AT_KROW + d0 * 32 + hi * 16);
;     p0 = MFMA(b0, qr[d0], p0);
;     p1 = MFMA(b1, qr[d0], p1);
;   }
; }
; __device__ __forceinline__ int v_st(int k, int c) { const int kk = (k & ~0xC) | ((k & 4) << 1) | ((k & 8) >> 1); return ((kk >> 3) * 4 + (c >> 5)) * 512 + ((kk & 7) * 32 + (c & 31)) * 2; }
; __device__ __forceinline__ int v_rd_base(int lane) { return ((lane & 3) << 3) | (((lane >> 2) & 3) << 6) | (((lane >> 4) & 1) << 5) | (((lane >> 5) & 1) << 8); }
; template <int OFF> __device__ __forceinline__ s16x4 tr_read(int vb) {
;   s16x4 r; asm volatile("ds_read_b64_tr_b16 %0, %1 offset:%2" : "=&v"(r) : "v"(vb), "i"(OFF) : "memory"); return r;
; }
; template <int D0> __device__ __forceinline__ void pv_one(f32x16& od, int vb, bf16x8 pa0, bf16x8 pa1, bf16x8 pa2, bf16x8 pa3) {
;   const s16x4 l0 = tr_read<v_rd_off(D0, 0, 0)>(vb), h0 = tr_read<v_rd_off(D0, 0, 1)>(vb), l1 = tr_read<v_rd_off(D0, 1, 0)>(vb), h1 = tr_read<v_rd_off(D0, 1, 1)>(vb);
;   const s16x4 l2 = tr_read<v_rd_off(D0, 2, 0)>(vb), h2 = tr_read<v_rd_off(D0, 2, 1)>(vb), l3 = tr_read<v_rd_off(D0, 3, 0)>(vb), h3 = tr_read<v_rd_off(D0, 3, 1)>(vb);
;   asm volatile("s_waitcnt lgkmcnt(0)" ::: "memory"); SBAR();
;     ...
;   od = MFMA(pa0, PK(l0, h0), od);
;   od = MFMA(pa1, PK(l1, h1), od);
;   od = MFMA(pa2, PK(l2, h2), od);
;   od = MFMA(pa3, PK(l3, h3), od);
;     ...
; }
; __device__ void phase_attn(const Params& p, char* lds) {
;     ...
;     for (int j = 1; j + 1 < NT; j += 2) {
;       SBAR(); at_qkt(pB0, pB1, K_lds + AT_SHMK, qr, r32, hi, -m_reg);
;       at_finishSM(pA0, pA1, alA, l_reg, pa0, pa1, pa2, pa3); SBAR();
;       SLOAD(1, (j + 2) * 64); SBAR();
;       pv_d0(o, vb0, pa0, pa1, pa2, pa3); at_partialSM(pB0, pB1, m_reg, alB, false);
;       __syncthreads(); SWAIT(); SWRITE(0, 0);
;       RESC(alB); __syncthreads();
.Lat_rare1_back:
	v_add_f32_e32 v173, v173, v175
	v_cvt_pk_bf16_f32 v104, v32, v33
	v_cvt_pk_bf16_f32 v105, v34, v35
	v_cvt_pk_bf16_f32 v106, v36, v37
	v_cvt_pk_bf16_f32 v107, v38, v39
	v_cvt_pk_bf16_f32 v108, v40, v41
	v_cvt_pk_bf16_f32 v109, v42, v43
	v_cvt_pk_bf16_f32 v110, v44, v45
	v_cvt_pk_bf16_f32 v111, v46, v47
	v_cvt_pk_bf16_f32 v112, v48, v49
	v_cvt_pk_bf16_f32 v113, v50, v51
	v_cvt_pk_bf16_f32 v114, v52, v53
	v_cvt_pk_bf16_f32 v115, v54, v55
	v_cvt_pk_bf16_f32 v116, v56, v57
	v_cvt_pk_bf16_f32 v117, v58, v59
	v_cvt_pk_bf16_f32 v118, v60, v61
	v_cvt_pk_bf16_f32 v119, v62, v63
	ds_read_b128 v[184:187], v170 offset:39936
	ds_read_b128 v[188:191], v170 offset:46592
	ds_read_b128 v[192:195], v170 offset:39968
	ds_read_b128 v[196:199], v170 offset:46624
	s_barrier
	ds_read_b128 v[200:203], v170 offset:40000
	ds_read_b128 v[204:207], v170 offset:46656
	s_waitcnt lgkmcnt(4)
	v_mfma_f32_32x32x16_bf16 v[32:47], v[184:187], v[80:83], v[64:79]
	v_mfma_f32_32x32x16_bf16 v[48:63], v[188:191], v[80:83], v[64:79]
	ds_read_b128 v[208:211], v170 offset:40032
	ds_read_b128 v[212:215], v170 offset:46688
	s_waitcnt lgkmcnt(4)
	v_mfma_f32_32x32x16_bf16 v[32:47], v[192:195], v[84:87], v[32:47]
	v_mfma_f32_32x32x16_bf16 v[48:63], v[196:199], v[84:87], v[48:63]
	ds_read_b128 v[184:187], v170 offset:40064
	ds_read_b128 v[188:191], v170 offset:46720
	s_waitcnt lgkmcnt(4)
	v_mfma_f32_32x32x16_bf16 v[32:47], v[200:203], v[88:91], v[32:47]
	v_mfma_f32_32x32x16_bf16 v[48:63], v[204:207], v[88:91], v[48:63]
	ds_read_b128 v[192:195], v170 offset:40096
	ds_read_b128 v[196:199], v170 offset:46752
	s_waitcnt lgkmcnt(4)
	v_mfma_f32_32x32x16_bf16 v[32:47], v[208:211], v[92:95], v[32:47]
	v_mfma_f32_32x32x16_bf16 v[48:63], v[212:215], v[92:95], v[48:63]
	ds_read_b64_tr_b16 v[148:149], v171 offset:32768
	ds_read_b64_tr_b16 v[150:151], v171 offset:34816
	ds_read_b64_tr_b16 v[152:153], v171 offset:36864
	ds_read_b64_tr_b16 v[154:155], v171 offset:38912
	s_waitcnt lgkmcnt(6)
	v_mfma_f32_32x32x16_bf16 v[32:47], v[184:187], v[96:99], v[32:47]
	v_mfma_f32_32x32x16_bf16 v[48:63], v[188:191], v[96:99], v[48:63]
	ds_read_b64_tr_b16 v[156:157], v171 offset:40960
	ds_read_b64_tr_b16 v[158:159], v171 offset:43008
	ds_read_b64_tr_b16 v[216:217], v171 offset:45056
	ds_read_b64_tr_b16 v[218:219], v171 offset:47104
	s_waitcnt lgkmcnt(8)
	v_mfma_f32_32x32x16_bf16 v[32:47], v[192:195], v[100:103], v[32:47]
	v_mfma_f32_32x32x16_bf16 v[48:63], v[196:199], v[100:103], v[48:63]
	ds_read_b64_tr_b16 v[220:221], v171 offset:33280
	ds_read_b64_tr_b16 v[222:223], v171 offset:35328
	ds_read_b64_tr_b16 v[224:225], v171 offset:37376
	ds_read_b64_tr_b16 v[226:227], v171 offset:39424
	s_waitcnt lgkmcnt(10)
	v_mfma_f32_32x32x16_bf16 v[0:15], v[104:107], v[148:151], v[0:15]
	s_waitcnt lgkmcnt(8)
	v_mfma_f32_32x32x16_bf16 v[0:15], v[108:111], v[152:155], v[0:15]
	ds_read_b64_tr_b16 v[236:237], v171 offset:41472
	ds_read_b64_tr_b16 v[238:239], v171 offset:43520
	ds_read_b64_tr_b16 v[240:241], v171 offset:45568
	ds_read_b64_tr_b16 v[242:243], v171 offset:47616
	s_waitcnt lgkmcnt(10)
	v_mfma_f32_32x32x16_bf16 v[0:15], v[112:115], v[156:159], v[0:15]
	s_waitcnt lgkmcnt(8)
	v_mfma_f32_32x32x16_bf16 v[0:15], v[116:119], v[216:219], v[0:15]
	s_waitcnt lgkmcnt(6)
	v_mfma_f32_32x32x16_bf16 v[16:31], v[104:107], v[220:223], v[16:31]
	s_waitcnt lgkmcnt(4)
	v_mfma_f32_32x32x16_bf16 v[16:31], v[108:111], v[224:227], v[16:31]
	s_waitcnt lgkmcnt(2)
	v_mfma_f32_32x32x16_bf16 v[16:31], v[112:115], v[236:239], v[16:31]
	s_waitcnt lgkmcnt(0)
	v_mfma_f32_32x32x16_bf16 v[16:31], v[116:119], v[240:243], v[16:31]
	s_barrier
	s_waitcnt vmcnt(0)
	s_add_i32 m0, s41, 0x16800
	s_cmp_lt_u32 s14, 5
	global_load_lds_dwordx4 v[246:247], off
	v_add_co_u32_e32 v246, vcc, v248, v246
	v_addc_co_u32_e32 v247, vcc, 0, v247, vcc
	s_cbranch_scc0 .Lat_kd7
	s_add_i32 m0, s30, 0x16800
	s_nop 0
	global_load_lds_dwordx4 v[250:251], off
.Lat_kd7:
	v_add_co_u32_e32 v250, vcc, v252, v250
	v_addc_co_u32_e32 v251, vcc, 0, v251, vcc
	s_add_i32 m0, s40, 0x4000
	s_nop 0
	global_load_lds_dwordx4 v131, s[36:37]
	s_add_u32 s36, s36, 0x40000
	s_addc_u32 s37, s37, 0
	v_exp_f32_e32 v32, v32
	v_exp_f32_e32 v48, v48
	v_exp_f32_e32 v33, v33
	v_exp_f32_e32 v49, v49
	v_exp_f32_e32 v34, v34
	v_exp_f32_e32 v50, v50
	v_exp_f32_e32 v35, v35
	v_exp_f32_e32 v51, v51
	v_exp_f32_e32 v36, v36
	v_exp_f32_e32 v52, v52
	v_exp_f32_e32 v37, v37
	v_exp_f32_e32 v53, v53
	v_exp_f32_e32 v38, v38
	v_exp_f32_e32 v54, v54
	v_exp_f32_e32 v39, v39
	v_exp_f32_e32 v55, v55
	v_exp_f32_e32 v40, v40
	v_exp_f32_e32 v56, v56
	v_exp_f32_e32 v41, v41
	v_exp_f32_e32 v57, v57
	v_exp_f32_e32 v42, v42
	v_exp_f32_e32 v58, v58
	v_exp_f32_e32 v43, v43
	v_exp_f32_e32 v59, v59
	v_exp_f32_e32 v44, v44
	v_exp_f32_e32 v60, v60
	v_exp_f32_e32 v45, v45
	v_exp_f32_e32 v61, v61
	v_exp_f32_e32 v46, v46
	v_exp_f32_e32 v62, v62
	v_exp_f32_e32 v47, v47
	v_exp_f32_e32 v63, v63
	v_add_f32_e32 v175, v32, v33
	v_add_f32_e32 v174, v48, v49
	v_add_f32_e32 v175, v175, v34
	v_add_f32_e32 v174, v174, v50
	v_add_f32_e32 v175, v175, v35
	v_add_f32_e32 v174, v174, v51
	v_add_f32_e32 v175, v175, v36
	v_add_f32_e32 v174, v174, v52
	v_add_f32_e32 v175, v175, v37
	v_add_f32_e32 v174, v174, v53
	v_add_f32_e32 v175, v175, v38
	v_add_f32_e32 v174, v174, v54
	v_add_f32_e32 v175, v175, v39
	v_add_f32_e32 v174, v174, v55
	v_add_f32_e32 v175, v175, v40
	v_add_f32_e32 v174, v174, v56
	v_add_f32_e32 v175, v175, v41
	v_add_f32_e32 v174, v174, v57
	v_add_f32_e32 v175, v175, v42
	v_add_f32_e32 v174, v174, v58
	v_add_f32_e32 v175, v175, v43
	v_add_f32_e32 v174, v174, v59
	v_add_f32_e32 v175, v175, v44
	v_add_f32_e32 v174, v174, v60
	v_add_f32_e32 v175, v175, v45
	v_add_f32_e32 v174, v174, v61
	v_add_f32_e32 v175, v175, v46
	v_add_f32_e32 v174, v174, v62
	v_add_f32_e32 v175, v175, v47
	v_add_f32_e32 v174, v174, v63
	v_add_f32_e32 v175, v175, v174
	v_cmp_ge_f32_e32 vcc, s23, v175
	s_cmp_eq_u64 vcc, exec
	s_cbranch_scc0 .Lat_rare2
; #define MFMA(a, b, c) __builtin_amdgcn_mfma_f32_32x32x16_bf16((a), (b), (c), 0, 0, 0)
; #define SBAR() __builtin_amdgcn_sched_barrier(0)
; #define SWAIT() asm volatile("s_waitcnt vmcnt(3)" ::: "memory")
; __device__ __forceinline__ void at_qkt(f32x16& p0, f32x16& p1, const char* Ks, const bf16x8* qr, int r32, int hi, float negm) {
; #pragma unroll
;   for (int r = 0; r < 16; ++r) { p0[r] = negm; p1[r] = negm; }
; #pragma unroll
;   for (int d0 = 0; d0 < 6; ++d0) {
;     const bf16x8 b0 = *(const bf16x8*)(Ks + r32 * AT_KROW + d0 * 32 + hi * 16);
;     const bf16x8 b1 = *(const bf16x8*)(Ks + (32 + r32) * AT_KROW + d0 * 32 + hi * 16);
;     p0 = MFMA(b0, qr[d0], p0);
;     p1 = MFMA(b1, qr[d0], p1);
;   }
; }
; __device__ __forceinline__ int v_st(int k, int c) { const int kk = (k & ~0xC) | ((k & 4) << 1) | ((k & 8) >> 1); return ((kk >> 3) * 4 + (c >> 5)) * 512 + ((kk & 7) * 32 + (c & 31)) * 2; }
; __device__ __forceinline__ int v_rd_base(int lane) { return ((lane & 3) << 3) | (((lane >> 2) & 3) << 6) | (((lane >> 4) & 1) << 5) | (((lane >> 5) & 1) << 8); }
; template <int OFF> __device__ __forceinline__ s16x4 tr_read(int vb) {
;   s16x4 r; asm volatile("ds_read_b64_tr_b16 %0, %1 offset:%2" : "=&v"(r) : "v"(vb), "i"(OFF) : "memory"); return r;
; }
; template <int D0> __device__ __forceinline__ void pv_one(f32x16& od, int vb, bf16x8 pa0, bf16x8 pa1, bf16x8 pa2, bf16x8 pa3) {
;   const s16x4 l0 = tr_read<v_rd_off(D0, 0, 0)>(vb), h0 = tr_read<v_rd_off(D0, 0, 1)>(vb), l1 = tr_read<v_rd_off(D0, 1, 0)>(vb), h1 = tr_read<v_rd_off(D0, 1, 1)>(vb);
;   const s16x4 l2 = tr_read<v_rd_off(D0, 2, 0)>(vb), h2 = tr_read<v_rd_off(D0, 2, 1)>(vb), l3 = tr_read<v_rd_off(D0, 3, 0)>(vb), h3 = tr_read<v_rd_off(D0, 3, 1)>(vb);
;   asm volatile("s_waitcnt lgkmcnt(0)" ::: "memory"); SBAR();
;     ...
;   od = MFMA(pa0, PK(l0, h0), od);
;   od = MFMA(pa1, PK(l1, h1), od);
;   od = MFMA(pa2, PK(l2, h2), od);
;   od = MFMA(pa3, PK(l3, h3), od);
;     ...
; }
; __device__ void phase_attn(const Params& p, char* lds) {
;     ...
;       SBAR(); at_qkt(pA0, pA1, K_lds, qr, r32, hi, -m_reg);
;       at_finishSM(pB0, pB1, alB, l_reg, pa0, pa1, pa2, pa3); SBAR();
;       if (j + 3 < NT) SLOAD(0, (j + 3) * 64); SBAR();
;       pv_d0(o, vb0 + AT_SHMV, pa0, pa1, pa2, pa3); at_partialSM(pA0, pA1, m_reg, alA, false);
;       __syncthreads(); SWAIT(); SWRITE(1, 1);
;       RESC(alA); __syncthreads();
.Lat_rare2_back:
	v_add_f32_e32 v173, v173, v175
	v_cvt_pk_bf16_f32 v104, v32, v33
	v_cvt_pk_bf16_f32 v105, v34, v35
	v_cvt_pk_bf16_f32 v106, v36, v37
	v_cvt_pk_bf16_f32 v107, v38, v39
	v_cvt_pk_bf16_f32 v108, v40, v41
	v_cvt_pk_bf16_f32 v109, v42, v43
	v_cvt_pk_bf16_f32 v110, v44, v45
	v_cvt_pk_bf16_f32 v111, v46, v47
	v_cvt_pk_bf16_f32 v112, v48, v49
	v_cvt_pk_bf16_f32 v113, v50, v51
	v_cvt_pk_bf16_f32 v114, v52, v53
	v_cvt_pk_bf16_f32 v115, v54, v55
	v_cvt_pk_bf16_f32 v116, v56, v57
	v_cvt_pk_bf16_f32 v117, v58, v59
	v_cvt_pk_bf16_f32 v118, v60, v61
	v_cvt_pk_bf16_f32 v119, v62, v63
	ds_read_b128 v[184:187], v170 offset:0
	ds_read_b128 v[188:191], v170 offset:6656
	ds_read_b128 v[192:195], v170 offset:32
	ds_read_b128 v[196:199], v170 offset:6688
	s_barrier
	ds_read_b128 v[200:203], v170 offset:64
	ds_read_b128 v[204:207], v170 offset:6720
	s_waitcnt lgkmcnt(4)
	v_mfma_f32_32x32x16_bf16 v[32:47], v[184:187], v[80:83], v[64:79]
	v_mfma_f32_32x32x16_bf16 v[48:63], v[188:191], v[80:83], v[64:79]
	ds_read_b128 v[208:211], v170 offset:96
	ds_read_b128 v[212:215], v170 offset:6752
	s_waitcnt lgkmcnt(4)
	v_mfma_f32_32x32x16_bf16 v[32:47], v[192:195], v[84:87], v[32:47]
	v_mfma_f32_32x32x16_bf16 v[48:63], v[196:199], v[84:87], v[48:63]
	ds_read_b128 v[184:187], v170 offset:128
	ds_read_b128 v[188:191], v170 offset:6784
	s_waitcnt lgkmcnt(4)
	v_mfma_f32_32x32x16_bf16 v[32:47], v[200:203], v[88:91], v[32:47]
	v_mfma_f32_32x32x16_bf16 v[48:63], v[204:207], v[88:91], v[48:63]
	ds_read_b128 v[192:195], v170 offset:160
	ds_read_b128 v[196:199], v170 offset:6816
	s_waitcnt lgkmcnt(4)
	v_mfma_f32_32x32x16_bf16 v[32:47], v[208:211], v[92:95], v[32:47]
	v_mfma_f32_32x32x16_bf16 v[48:63], v[212:215], v[92:95], v[48:63]
	ds_read_b64_tr_b16 v[148:149], v171 offset:49152
	ds_read_b64_tr_b16 v[150:151], v171 offset:51200
	ds_read_b64_tr_b16 v[152:153], v171 offset:53248
	ds_read_b64_tr_b16 v[154:155], v171 offset:55296
	s_waitcnt lgkmcnt(6)
	v_mfma_f32_32x32x16_bf16 v[32:47], v[184:187], v[96:99], v[32:47]
	v_mfma_f32_32x32x16_bf16 v[48:63], v[188:191], v[96:99], v[48:63]
	ds_read_b64_tr_b16 v[156:157], v171 offset:57344
	ds_read_b64_tr_b16 v[158:159], v171 offset:59392
	ds_read_b64_tr_b16 v[216:217], v171 offset:61440
	ds_read_b64_tr_b16 v[218:219], v171 offset:63488
	s_waitcnt lgkmcnt(8)
	v_mfma_f32_32x32x16_bf16 v[32:47], v[192:195], v[100:103], v[32:47]
	v_mfma_f32_32x32x16_bf16 v[48:63], v[196:199], v[100:103], v[48:63]
	ds_read_b64_tr_b16 v[220:221], v171 offset:49664
	ds_read_b64_tr_b16 v[222:223], v171 offset:51712
	ds_read_b64_tr_b16 v[224:225], v171 offset:53760
	ds_read_b64_tr_b16 v[226:227], v171 offset:55808
	s_waitcnt lgkmcnt(10)
	v_mfma_f32_32x32x16_bf16 v[0:15], v[104:107], v[148:151], v[0:15]
	s_waitcnt lgkmcnt(8)
	v_mfma_f32_32x32x16_bf16 v[0:15], v[108:111], v[152:155], v[0:15]
	ds_read_b64_tr_b16 v[236:237], v171 offset:57856
	ds_read_b64_tr_b16 v[238:239], v171 offset:59904
	ds_read_b64_tr_b16 v[240:241], v171 offset:61952
	ds_read_b64_tr_b16 v[242:243], v171 offset:64000
	s_waitcnt lgkmcnt(10)
	v_mfma_f32_32x32x16_bf16 v[0:15], v[112:115], v[156:159], v[0:15]
	s_waitcnt lgkmcnt(8)
	v_mfma_f32_32x32x16_bf16 v[0:15], v[116:119], v[216:219], v[0:15]
	s_waitcnt lgkmcnt(6)
	v_mfma_f32_32x32x16_bf16 v[16:31], v[104:107], v[220:223], v[16:31]
	s_waitcnt lgkmcnt(4)
	v_mfma_f32_32x32x16_bf16 v[16:31], v[108:111], v[224:227], v[16:31]
	s_waitcnt lgkmcnt(2)
	v_mfma_f32_32x32x16_bf16 v[16:31], v[112:115], v[236:239], v[16:31]
	s_waitcnt lgkmcnt(0)
	v_mfma_f32_32x32x16_bf16 v[16:31], v[116:119], v[240:243], v[16:31]
	s_barrier
	s_waitcnt vmcnt(0)
	s_add_i32 m0, s41, 0x19c00
	s_cmp_lt_u32 s14, 5
	global_load_lds_dwordx4 v[246:247], off
	v_add_co_u32_e32 v246, vcc, v248, v246
	v_addc_co_u32_e32 v247, vcc, 0, v247, vcc
	s_cbranch_scc0 .Lat_kd8
	s_add_i32 m0, s30, 0x19c00
	s_nop 0
	global_load_lds_dwordx4 v[250:251], off
.Lat_kd8:
	v_add_co_u32_e32 v250, vcc, v252, v250
	v_addc_co_u32_e32 v251, vcc, 0, v251, vcc
	s_add_i32 m0, s40, 0x8000
	s_nop 0
	global_load_lds_dwordx4 v131, s[36:37]
	s_add_u32 s36, s36, 0x40000
	s_addc_u32 s37, s37, 0
	v_exp_f32_e32 v32, v32
	v_exp_f32_e32 v48, v48
	v_exp_f32_e32 v33, v33
	v_exp_f32_e32 v49, v49
	v_exp_f32_e32 v34, v34
	v_exp_f32_e32 v50, v50
	v_exp_f32_e32 v35, v35
	v_exp_f32_e32 v51, v51
	v_exp_f32_e32 v36, v36
	v_exp_f32_e32 v52, v52
	v_exp_f32_e32 v37, v37
	v_exp_f32_e32 v53, v53
	v_exp_f32_e32 v38, v38
	v_exp_f32_e32 v54, v54
	v_exp_f32_e32 v39, v39
	v_exp_f32_e32 v55, v55
	v_exp_f32_e32 v40, v40
	v_exp_f32_e32 v56, v56
	v_exp_f32_e32 v41, v41
	v_exp_f32_e32 v57, v57
	v_exp_f32_e32 v42, v42
	v_exp_f32_e32 v58, v58
	v_exp_f32_e32 v43, v43
	v_exp_f32_e32 v59, v59
	v_exp_f32_e32 v44, v44
	v_exp_f32_e32 v60, v60
	v_exp_f32_e32 v45, v45
	v_exp_f32_e32 v61, v61
	v_exp_f32_e32 v46, v46
	v_exp_f32_e32 v62, v62
	v_exp_f32_e32 v47, v47
	v_exp_f32_e32 v63, v63
	v_add_f32_e32 v175, v32, v33
	v_add_f32_e32 v174, v48, v49
	v_add_f32_e32 v175, v175, v34
	v_add_f32_e32 v174, v174, v50
	v_add_f32_e32 v175, v175, v35
	v_add_f32_e32 v174, v174, v51
	v_add_f32_e32 v175, v175, v36
	v_add_f32_e32 v174, v174, v52
	v_add_f32_e32 v175, v175, v37
	v_add_f32_e32 v174, v174, v53
	v_add_f32_e32 v175, v175, v38
	v_add_f32_e32 v174, v174, v54
	v_add_f32_e32 v175, v175, v39
	v_add_f32_e32 v174, v174, v55
	v_add_f32_e32 v175, v175, v40
	v_add_f32_e32 v174, v174, v56
	v_add_f32_e32 v175, v175, v41
	v_add_f32_e32 v174, v174, v57
	v_add_f32_e32 v175, v175, v42
	v_add_f32_e32 v174, v174, v58
	v_add_f32_e32 v175, v175, v43
	v_add_f32_e32 v174, v174, v59
	v_add_f32_e32 v175, v175, v44
	v_add_f32_e32 v174, v174, v60
	v_add_f32_e32 v175, v175, v45
	v_add_f32_e32 v174, v174, v61
	v_add_f32_e32 v175, v175, v46
	v_add_f32_e32 v174, v174, v62
	v_add_f32_e32 v175, v175, v47
	v_add_f32_e32 v174, v174, v63
	v_add_f32_e32 v175, v175, v174
	v_cmp_ge_f32_e32 vcc, s23, v175
	s_cmp_eq_u64 vcc, exec
	s_cbranch_scc0 .Lat_rare3
; #define MFMA(a, b, c) __builtin_amdgcn_mfma_f32_32x32x16_bf16((a), (b), (c), 0, 0, 0)
; #define SBAR() __builtin_amdgcn_sched_barrier(0)
; __device__ __forceinline__ void at_qkt(f32x16& p0, f32x16& p1, const char* Ks, const bf16x8* qr, int r32, int hi, float negm) {
; #pragma unroll
;   for (int r = 0; r < 16; ++r) { p0[r] = negm; p1[r] = negm; }
; #pragma unroll
;   for (int d0 = 0; d0 < 6; ++d0) {
;     const bf16x8 b0 = *(const bf16x8*)(Ks + r32 * AT_KROW + d0 * 32 + hi * 16);
;     const bf16x8 b1 = *(const bf16x8*)(Ks + (32 + r32) * AT_KROW + d0 * 32 + hi * 16);
;     p0 = MFMA(b0, qr[d0], p0);
;     p1 = MFMA(b1, qr[d0], p1);
;   }
; }
; __device__ __forceinline__ int v_st(int k, int c) { const int kk = (k & ~0xC) | ((k & 4) << 1) | ((k & 8) >> 1); return ((kk >> 3) * 4 + (c >> 5)) * 512 + ((kk & 7) * 32 + (c & 31)) * 2; }
; __device__ __forceinline__ int v_rd_base(int lane) { return ((lane & 3) << 3) | (((lane >> 2) & 3) << 6) | (((lane >> 4) & 1) << 5) | (((lane >> 5) & 1) << 8); }
; template <int OFF> __device__ __forceinline__ s16x4 tr_read(int vb) {
;   s16x4 r; asm volatile("ds_read_b64_tr_b16 %0, %1 offset:%2" : "=&v"(r) : "v"(vb), "i"(OFF) : "memory"); return r;
; }
; template <int D0> __device__ __forceinline__ void pv_one(f32x16& od, int vb, bf16x8 pa0, bf16x8 pa1, bf16x8 pa2, bf16x8 pa3) {
;   const s16x4 l0 = tr_read<v_rd_off(D0, 0, 0)>(vb), h0 = tr_read<v_rd_off(D0, 0, 1)>(vb), l1 = tr_read<v_rd_off(D0, 1, 0)>(vb), h1 = tr_read<v_rd_off(D0, 1, 1)>(vb);
;   const s16x4 l2 = tr_read<v_rd_off(D0, 2, 0)>(vb), h2 = tr_read<v_rd_off(D0, 2, 1)>(vb), l3 = tr_read<v_rd_off(D0, 3, 0)>(vb), h3 = tr_read<v_rd_off(D0, 3, 1)>(vb);
;   asm volatile("s_waitcnt lgkmcnt(0)" ::: "memory"); SBAR();
;     ...
;   od = MFMA(pa0, PK(l0, h0), od);
;   od = MFMA(pa1, PK(l1, h1), od);
;   od = MFMA(pa2, PK(l2, h2), od);
;   od = MFMA(pa3, PK(l3, h3), od);
;     ...
; }
; __device__ void phase_attn(const Params& p, char* lds) {
;     ...
;       RESC(alA); __syncthreads();
;     }
;     SBAR(); at_qkt(pB0, pB1, K_lds + AT_SHMK, qr, r32, hi, -m_reg);
;     at_finishSM(pA0, pA1, alA, l_reg, pa0, pa1, pa2, pa3); SBAR();
;     pv_d0(o, vb0, pa0, pa1, pa2, pa3); at_partialSM(pB0, pB1, m_reg, alB, false);
;     __syncthreads(); RESC(alB);
.Lat_rare3_back:
	v_add_f32_e32 v173, v173, v175
	v_cvt_pk_bf16_f32 v104, v32, v33
	v_cvt_pk_bf16_f32 v105, v34, v35
	v_cvt_pk_bf16_f32 v106, v36, v37
	v_cvt_pk_bf16_f32 v107, v38, v39
	v_cvt_pk_bf16_f32 v108, v40, v41
	v_cvt_pk_bf16_f32 v109, v42, v43
	v_cvt_pk_bf16_f32 v110, v44, v45
	v_cvt_pk_bf16_f32 v111, v46, v47
	v_cvt_pk_bf16_f32 v112, v48, v49
	v_cvt_pk_bf16_f32 v113, v50, v51
	v_cvt_pk_bf16_f32 v114, v52, v53
	v_cvt_pk_bf16_f32 v115, v54, v55
	v_cvt_pk_bf16_f32 v116, v56, v57
	v_cvt_pk_bf16_f32 v117, v58, v59
	v_cvt_pk_bf16_f32 v118, v60, v61
	v_cvt_pk_bf16_f32 v119, v62, v63
	ds_read_b128 v[184:187], v170 offset:13312
	ds_read_b128 v[188:191], v170 offset:19968
	ds_read_b128 v[192:195], v170 offset:13344
	ds_read_b128 v[196:199], v170 offset:20000
	s_barrier
	s_sub_u32 s13, s13, 1
	s_cmp_lg_u32 s13, 0
	s_cbranch_scc1 .Lat_loop
	ds_read_b128 v[200:203], v170 offset:13376
	ds_read_b128 v[204:207], v170 offset:20032
	s_waitcnt lgkmcnt(4)
	v_mfma_f32_32x32x16_bf16 v[32:47], v[184:187], v[80:83], v[64:79]
	v_mfma_f32_32x32x16_bf16 v[48:63], v[188:191], v[80:83], v[64:79]
	ds_read_b128 v[208:211], v170 offset:13408
	ds_read_b128 v[212:215], v170 offset:20064
	s_waitcnt lgkmcnt(4)
	v_mfma_f32_32x32x16_bf16 v[32:47], v[192:195], v[84:87], v[32:47]
	v_mfma_f32_32x32x16_bf16 v[48:63], v[196:199], v[84:87], v[48:63]
	ds_read_b128 v[184:187], v170 offset:13440
	ds_read_b128 v[188:191], v170 offset:20096
	s_waitcnt lgkmcnt(4)
	v_mfma_f32_32x32x16_bf16 v[32:47], v[200:203], v[88:91], v[32:47]
	v_mfma_f32_32x32x16_bf16 v[48:63], v[204:207], v[88:91], v[48:63]
	ds_read_b128 v[192:195], v170 offset:13472
	ds_read_b128 v[196:199], v170 offset:20128
	s_waitcnt lgkmcnt(4)
	v_mfma_f32_32x32x16_bf16 v[32:47], v[208:211], v[92:95], v[32:47]
	v_mfma_f32_32x32x16_bf16 v[48:63], v[212:215], v[92:95], v[48:63]
	ds_read_b64_tr_b16 v[148:149], v171 offset:0
	ds_read_b64_tr_b16 v[150:151], v171 offset:2048
	ds_read_b64_tr_b16 v[152:153], v171 offset:4096
	ds_read_b64_tr_b16 v[154:155], v171 offset:6144
	s_waitcnt lgkmcnt(6)
	v_mfma_f32_32x32x16_bf16 v[32:47], v[184:187], v[96:99], v[32:47]
	v_mfma_f32_32x32x16_bf16 v[48:63], v[188:191], v[96:99], v[48:63]
	ds_read_b64_tr_b16 v[156:157], v171 offset:8192
	ds_read_b64_tr_b16 v[158:159], v171 offset:10240
	ds_read_b64_tr_b16 v[216:217], v171 offset:12288
	ds_read_b64_tr_b16 v[218:219], v171 offset:14336
	s_waitcnt lgkmcnt(8)
	v_mfma_f32_32x32x16_bf16 v[32:47], v[192:195], v[100:103], v[32:47]
	v_mfma_f32_32x32x16_bf16 v[48:63], v[196:199], v[100:103], v[48:63]
	ds_read_b64_tr_b16 v[220:221], v171 offset:512
	ds_read_b64_tr_b16 v[222:223], v171 offset:2560
	ds_read_b64_tr_b16 v[224:225], v171 offset:4608
	ds_read_b64_tr_b16 v[226:227], v171 offset:6656
	s_waitcnt lgkmcnt(10)
	v_mfma_f32_32x32x16_bf16 v[0:15], v[104:107], v[148:151], v[0:15]
	s_waitcnt lgkmcnt(8)
	v_mfma_f32_32x32x16_bf16 v[0:15], v[108:111], v[152:155], v[0:15]
	ds_read_b64_tr_b16 v[236:237], v171 offset:8704
	ds_read_b64_tr_b16 v[238:239], v171 offset:10752
	ds_read_b64_tr_b16 v[240:241], v171 offset:12800
	ds_read_b64_tr_b16 v[242:243], v171 offset:14848
	s_waitcnt lgkmcnt(10)
	v_mfma_f32_32x32x16_bf16 v[0:15], v[112:115], v[156:159], v[0:15]
	s_waitcnt lgkmcnt(8)
	v_mfma_f32_32x32x16_bf16 v[0:15], v[116:119], v[216:219], v[0:15]
	s_waitcnt lgkmcnt(6)
	v_mfma_f32_32x32x16_bf16 v[16:31], v[104:107], v[220:223], v[16:31]
	s_waitcnt lgkmcnt(4)
	v_mfma_f32_32x32x16_bf16 v[16:31], v[108:111], v[224:227], v[16:31]
	s_waitcnt lgkmcnt(2)
	v_mfma_f32_32x32x16_bf16 v[16:31], v[112:115], v[236:239], v[16:31]
	s_waitcnt lgkmcnt(0)
	v_mfma_f32_32x32x16_bf16 v[16:31], v[116:119], v[240:243], v[16:31]
	s_barrier
	s_waitcnt vmcnt(0)
	s_add_i32 m0, s40, 0xc000
	s_nop 0
	global_load_lds_dwordx4 v131, s[36:37]
	s_add_u32 s36, s36, 0x40000
	s_addc_u32 s37, s37, 0
	v_exp_f32_e32 v32, v32
	v_exp_f32_e32 v48, v48
	v_exp_f32_e32 v33, v33
	v_exp_f32_e32 v49, v49
	v_exp_f32_e32 v34, v34
	v_exp_f32_e32 v50, v50
	v_exp_f32_e32 v35, v35
	v_exp_f32_e32 v51, v51
	v_exp_f32_e32 v36, v36
	v_exp_f32_e32 v52, v52
	v_exp_f32_e32 v37, v37
	v_exp_f32_e32 v53, v53
	v_exp_f32_e32 v38, v38
	v_exp_f32_e32 v54, v54
	v_exp_f32_e32 v39, v39
	v_exp_f32_e32 v55, v55
	v_exp_f32_e32 v40, v40
	v_exp_f32_e32 v56, v56
	v_exp_f32_e32 v41, v41
	v_exp_f32_e32 v57, v57
	v_exp_f32_e32 v42, v42
	v_exp_f32_e32 v58, v58
	v_exp_f32_e32 v43, v43
	v_exp_f32_e32 v59, v59
	v_exp_f32_e32 v44, v44
	v_exp_f32_e32 v60, v60
	v_exp_f32_e32 v45, v45
	v_exp_f32_e32 v61, v61
	v_exp_f32_e32 v46, v46
	v_exp_f32_e32 v62, v62
	v_exp_f32_e32 v47, v47
	v_exp_f32_e32 v63, v63
	v_add_f32_e32 v175, v32, v33
	v_add_f32_e32 v174, v48, v49
	v_add_f32_e32 v175, v175, v34
	v_add_f32_e32 v174, v174, v50
	v_add_f32_e32 v175, v175, v35
	v_add_f32_e32 v174, v174, v51
	v_add_f32_e32 v175, v175, v36
	v_add_f32_e32 v174, v174, v52
	v_add_f32_e32 v175, v175, v37
	v_add_f32_e32 v174, v174, v53
	v_add_f32_e32 v175, v175, v38
	v_add_f32_e32 v174, v174, v54
	v_add_f32_e32 v175, v175, v39
	v_add_f32_e32 v174, v174, v55
	v_add_f32_e32 v175, v175, v40
	v_add_f32_e32 v174, v174, v56
	v_add_f32_e32 v175, v175, v41
	v_add_f32_e32 v174, v174, v57
	v_add_f32_e32 v175, v175, v42
	v_add_f32_e32 v174, v174, v58
	v_add_f32_e32 v175, v175, v43
	v_add_f32_e32 v174, v174, v59
	v_add_f32_e32 v175, v175, v44
	v_add_f32_e32 v174, v174, v60
	v_add_f32_e32 v175, v175, v45
	v_add_f32_e32 v174, v174, v61
	v_add_f32_e32 v175, v175, v46
	v_add_f32_e32 v174, v174, v62
	v_add_f32_e32 v175, v175, v47
	v_add_f32_e32 v174, v174, v63
	v_add_f32_e32 v175, v175, v174
	v_cmp_ge_f32_e32 vcc, s23, v175
	s_cmp_eq_u64 vcc, exec
	s_cbranch_scc0 .Lat_rare_t129
